# Gray-walk MFMA order (consecutive MFMAs share accumulator or an operand) + 64-bit zeroing of accumulators
# speedup vs baseline: 1.0183x; 1.0132x over previous
; #define PG8_STAGE(bufoff, gbase, voff) do { _Pragma("unroll") for (int _i = 0; _i < 2; ++_i) \
;         __builtin_amdgcn_global_load_lds((const unsigned*)((const char*)(gbase) + (voff)[_i]), (PG8_LAS unsigned*)(lds + (bufoff) + ldsw + _i * 8192), 16, 0, 0); } while (0)
; #define PG8_LDA(dst, b, h) do { _Pragma("unroll") for (int m = 0; m < 4; ++m) _Pragma("unroll") for (int k = 0; k < 2; ++k) dst[m][k] = *(const PG8_LAS bf16x8*)(lds + PG8_SA(b, h) + aoff + m * 2048 + k * 1024); } while (0)
; #define PG8_LDB(dst, b, h) do { _Pragma("unroll") for (int n = 0; n < 2; ++n) _Pragma("unroll") for (int k = 0; k < 2; ++k) dst[n][k] = *(const PG8_LAS bf16x8*)(lds + PG8_SB(b, h) + boff + n * 2048 + k * 1024); } while (0)
; #define PG8_WAIT_V(n) asm volatile("s_waitcnt vmcnt(" #n ")" ::: "memory")
; #define PG8_WAIT_L(n) asm volatile("s_waitcnt lgkmcnt(" #n ")" ::: "memory")
; #define PG8_BAR __builtin_amdgcn_s_barrier()
; #define PG8_SCHED __builtin_amdgcn_sched_barrier(0)
; template <class Epi, class Sched, bool ALIGN_EPI = false, bool SP2 = false>
; __device__ __forceinline__ void gemm_phase(PG8_LAS unsigned char* lds, const Gemm g, const Sched& S, const Epi& E) {
;     ...
;         const char* nA = has_next ? (const char*)g.A + (size_t)nxt.pm * tstep : cA; const char* nB = has_next ? (const char*)g.Bt + (size_t)nxt.pn * tstep : cB;
;         for (int t = 0; t < nt; t += 2) {
;             const bool last = (t == nt - 2);
;             const char* a1 = cA + (size_t)(t + 1) * kstepA;
;             const char* a2 = last ? nA : cA + (size_t)(t + 2) * kstepA; const char* b2 = last ? nB : cB + (size_t)(t + 2) * kstep;
;             const char* a3 = a2 + kstepA; const char* b3 = b2 + kstep;
;             if (last && has_next) S.a_ready(nxt);
;             if constexpr (SP2) {
;             PG8_LDB(B0, 0, 0); PG8_LDB(B1, 0, 1); PG8_SCHED; PG8_LDA(At, 0, 0); PG8_STAGE(PG8_SA(1, 1), a1 + hstep, voffA);
;             PG8_WAIT_V(8); PG8_WAIT_L(0); PG8_BAR; PG8_MMA(0, 0, At, B0); PG8_MMA(0, 1, At, B1); PG8_BAR; PG8_SCHED;
;     ...
; #pragma unroll
;         for (int a = 0; a < 2; ++a)
; #pragma unroll
;             for (int b = 0; b < 2; ++b)
; #pragma unroll
;                 for (int m = 0; m < 4; ++m)
; #pragma unroll
;                     for (int n = 0; n < 2; ++n) acc[a][b][m][n] = (f32x4){0.f, 0.f, 0.f, 0.f};
.LBB0_237:
	s_ashr_i32 s11, s10, 31
	s_lshl_b64 s[2:3], s[10:11], 19
	s_add_u32 s12, s52, s2
	s_addc_u32 s13, s53, s3
	s_and_b64 s[2:3], s[40:41], exec
	s_cselect_b32 s11, s13, s25
	s_cselect_b32 s67, s12, s24
	s_ashr_i32 s9, s8, 31
	s_lshl_b64 s[2:3], s[8:9], 19
	s_add_u32 s44, s54, s2
	s_addc_u32 s45, s55, s3
	s_and_b64 s[2:3], s[40:41], exec
	s_cselect_b32 s9, s45, s27
	s_cselect_b32 s68, s44, s26
	s_add_u32 s69, s26, 0x100
	v_mov_b64_e32 v[2:3], 0
	v_mov_b64_e32 v[4:5], 0
	v_mov_b64_e32 v[6:7], 0
	v_mov_b64_e32 v[8:9], 0
	v_mov_b64_e32 v[10:11], 0
	v_mov_b64_e32 v[12:13], 0
	v_mov_b64_e32 v[14:15], 0
	v_mov_b64_e32 v[16:17], 0
	v_mov_b64_e32 v[18:19], 0
	v_mov_b64_e32 v[20:21], 0
	v_mov_b64_e32 v[22:23], 0
	v_mov_b64_e32 v[24:25], 0
	v_mov_b64_e32 v[26:27], 0
	v_mov_b64_e32 v[28:29], 0
	v_mov_b64_e32 v[30:31], 0
	v_mov_b64_e32 v[32:33], 0
	v_mov_b64_e32 v[34:35], 0
	v_mov_b64_e32 v[36:37], 0
	v_mov_b64_e32 v[38:39], 0
	v_mov_b64_e32 v[40:41], 0
	v_mov_b64_e32 v[42:43], 0
	v_mov_b64_e32 v[44:45], 0
	v_mov_b64_e32 v[46:47], 0
	v_mov_b64_e32 v[48:49], 0
	v_mov_b64_e32 v[50:51], 0
	v_mov_b64_e32 v[52:53], 0
	v_mov_b64_e32 v[54:55], 0
	v_mov_b64_e32 v[56:57], 0
	v_mov_b64_e32 v[58:59], 0
	v_mov_b64_e32 v[60:61], 0
	v_mov_b64_e32 v[62:63], 0
	v_mov_b64_e32 v[64:65], 0
	v_mov_b64_e32 v[66:67], 0
	v_mov_b64_e32 v[68:69], 0
	v_mov_b64_e32 v[70:71], 0
	v_mov_b64_e32 v[72:73], 0
	v_mov_b64_e32 v[74:75], 0
	v_mov_b64_e32 v[76:77], 0
	v_mov_b64_e32 v[78:79], 0
	v_mov_b64_e32 v[80:81], 0
	v_mov_b64_e32 v[82:83], 0
	v_mov_b64_e32 v[84:85], 0
	v_mov_b64_e32 v[86:87], 0
	v_mov_b64_e32 v[88:89], 0
	v_mov_b64_e32 v[90:91], 0
	v_mov_b64_e32 v[92:93], 0
	v_mov_b64_e32 v[94:95], 0
	v_mov_b64_e32 v[96:97], 0
	v_mov_b64_e32 v[98:99], 0
	v_mov_b64_e32 v[100:101], 0
	v_mov_b64_e32 v[102:103], 0
	v_mov_b64_e32 v[104:105], 0
	v_mov_b64_e32 v[106:107], 0
	v_mov_b64_e32 v[108:109], 0
	v_mov_b64_e32 v[110:111], 0
	v_mov_b64_e32 v[112:113], 0
	v_mov_b64_e32 v[114:115], 0
	v_mov_b64_e32 v[116:117], 0
	v_mov_b64_e32 v[118:119], 0
	v_mov_b64_e32 v[120:121], 0
	v_mov_b64_e32 v[122:123], 0
	v_mov_b64_e32 v[124:125], 0
	v_mov_b64_e32 v[126:127], 0
	v_mov_b64_e32 v[128:129], 0
	s_addc_u32 s70, s27, 0
	s_mov_b32 s71, -2
.LBB0_238:
	s_add_u32 s2, s24, 0x8000
	s_addc_u32 s3, s25, 0
	s_cmp_eq_u32 s71, 12
	s_cselect_b32 s46, s67, s2
	s_cselect_b32 s47, s11, s3
	s_cselect_b32 s42, s68, s69
	s_cselect_b32 s43, s9, s70
	s_add_u32 s26, s46, 0x4000
	s_addc_u32 s27, s47, 0
	v_add_u32_e32 v148, s76, v150
	s_add_i32 s72, 0, 0x14000
	ds_read_b128 v[144:147], v148
	ds_read_b128 v[160:163], v148 offset:1024
	ds_read_b128 v[164:167], v148 offset:2048
	ds_read_b128 v[168:171], v148 offset:3072
	v_add_u32_e32 v148, s72, v150
	ds_read_b128 v[172:175], v148
	ds_read_b128 v[176:179], v148 offset:1024
	ds_read_b128 v[180:183], v148 offset:2048
	ds_read_b128 v[184:187], v148 offset:3072
	v_lshl_add_u64 v[148:149], s[24:25], 0, v[142:143]
	s_add_i32 m0, s23, 0xc000
	ds_read_b128 v[188:191], v152
	ds_read_b128 v[206:209], v152 offset:1024
	ds_read_b128 v[210:213], v152 offset:2048
	ds_read_b128 v[214:217], v152 offset:3072
	ds_read_b128 v[218:221], v152 offset:4096
	ds_read_b128 v[222:225], v152 offset:5120
	ds_read_b128 v[226:229], v152 offset:6144
	ds_read_b128 v[230:233], v152 offset:7168
	global_load_lds_dwordx4 v[148:149], off
	v_lshl_add_u64 v[148:149], s[24:25], 0, v[140:141]
	s_add_i32 m0, s23, 0xe000
	s_nop 0
	global_load_lds_dwordx4 v[148:149], off
	s_waitcnt vmcnt(8)
	s_waitcnt lgkmcnt(0)
	s_barrier
	s_setprio 1
	s_waitcnt lgkmcnt(0)
	v_mfma_f32_16x16x32_bf16 v[126:129], v[144:147], v[188:191], v[126:129]
	v_mfma_f32_16x16x32_bf16 v[126:129], v[160:163], v[206:209], v[126:129]
	v_mfma_f32_16x16x32_bf16 v[122:125], v[168:171], v[206:209], v[122:125]
	v_mfma_f32_16x16x32_bf16 v[122:125], v[164:167], v[188:191], v[122:125]
	v_mfma_f32_16x16x32_bf16 v[106:109], v[164:167], v[210:213], v[106:109]
	v_mfma_f32_16x16x32_bf16 v[106:109], v[168:171], v[214:217], v[106:109]
	v_mfma_f32_16x16x32_bf16 v[110:113], v[160:163], v[214:217], v[110:113]
	v_mfma_f32_16x16x32_bf16 v[110:113], v[144:147], v[210:213], v[110:113]
	v_mfma_f32_16x16x32_bf16 v[94:97], v[144:147], v[218:221], v[94:97]
	v_mfma_f32_16x16x32_bf16 v[94:97], v[160:163], v[222:225], v[94:97]
	v_mfma_f32_16x16x32_bf16 v[90:93], v[168:171], v[222:225], v[90:93]
	v_mfma_f32_16x16x32_bf16 v[90:93], v[164:167], v[218:221], v[90:93]
	v_mfma_f32_16x16x32_bf16 v[74:77], v[164:167], v[226:229], v[74:77]
	v_mfma_f32_16x16x32_bf16 v[74:77], v[168:171], v[230:233], v[74:77]
	v_mfma_f32_16x16x32_bf16 v[78:81], v[160:163], v[230:233], v[78:81]
	v_mfma_f32_16x16x32_bf16 v[78:81], v[144:147], v[226:229], v[78:81]
	s_setprio 0
	s_setprio 1
	v_mfma_f32_16x16x32_bf16 v[118:121], v[172:175], v[188:191], v[118:121]
	v_mfma_f32_16x16x32_bf16 v[118:121], v[176:179], v[206:209], v[118:121]
	v_mfma_f32_16x16x32_bf16 v[114:117], v[184:187], v[206:209], v[114:117]
	v_mfma_f32_16x16x32_bf16 v[114:117], v[180:183], v[188:191], v[114:117]
	v_mfma_f32_16x16x32_bf16 v[98:101], v[180:183], v[210:213], v[98:101]
	v_mfma_f32_16x16x32_bf16 v[98:101], v[184:187], v[214:217], v[98:101]
	v_mfma_f32_16x16x32_bf16 v[102:105], v[176:179], v[214:217], v[102:105]
	v_mfma_f32_16x16x32_bf16 v[102:105], v[172:175], v[210:213], v[102:105]
	v_mfma_f32_16x16x32_bf16 v[86:89], v[172:175], v[218:221], v[86:89]
	v_mfma_f32_16x16x32_bf16 v[86:89], v[176:179], v[222:225], v[86:89]
	v_mfma_f32_16x16x32_bf16 v[82:85], v[184:187], v[222:225], v[82:85]
	v_mfma_f32_16x16x32_bf16 v[82:85], v[180:183], v[218:221], v[82:85]
	v_mfma_f32_16x16x32_bf16 v[66:69], v[180:183], v[226:229], v[66:69]
	v_mfma_f32_16x16x32_bf16 v[66:69], v[184:187], v[230:233], v[66:69]
	v_mfma_f32_16x16x32_bf16 v[70:73], v[176:179], v[230:233], v[70:73]
	v_mfma_f32_16x16x32_bf16 v[70:73], v[172:175], v[226:229], v[70:73]
	s_setprio 0
	s_barrier
; #define PG8_STAGE(bufoff, gbase, voff) do { _Pragma("unroll") for (int _i = 0; _i < 2; ++_i) \
;         __builtin_amdgcn_global_load_lds((const unsigned*)((const char*)(gbase) + (voff)[_i]), (PG8_LAS unsigned*)(lds + (bufoff) + ldsw + _i * 8192), 16, 0, 0); } while (0)
; #define PG8_LDA(dst, b, h) do { _Pragma("unroll") for (int m = 0; m < 4; ++m) _Pragma("unroll") for (int k = 0; k < 2; ++k) dst[m][k] = *(const PG8_LAS bf16x8*)(lds + PG8_SA(b, h) + aoff + m * 2048 + k * 1024); } while (0)
; #define PG8_LDB(dst, b, h) do { _Pragma("unroll") for (int n = 0; n < 2; ++n) _Pragma("unroll") for (int k = 0; k < 2; ++k) dst[n][k] = *(const PG8_LAS bf16x8*)(lds + PG8_SB(b, h) + boff + n * 2048 + k * 1024); } while (0)
; #define PG8_MMA(ai, bj, At, Bt) do { __builtin_amdgcn_s_setprio(1); _Pragma("unroll") for (int m = 0; m < 4; ++m) _Pragma("unroll") for (int n = 0; n < 2; ++n) _Pragma("unroll") for (int k = 0; k < 2; ++k) \
;         acc[ai][bj][m][n] = __builtin_amdgcn_mfma_f32_16x16x32_bf16(Bt[n][k], At[m][k], acc[ai][bj][m][n], 0, 0, 0); __builtin_amdgcn_s_setprio(0); } while (0)
; #define PG8_WAIT_V(n) asm volatile("s_waitcnt vmcnt(" #n ")" ::: "memory")
; #define PG8_WAIT_L(n) asm volatile("s_waitcnt lgkmcnt(" #n ")" ::: "memory")
; #define PG8_BAR __builtin_amdgcn_s_barrier()
; #define PG8_SCHED __builtin_amdgcn_sched_barrier(0)
; template <class Epi, class Sched, bool ALIGN_EPI = false, bool SP2 = false>
; __device__ __forceinline__ void gemm_phase(PG8_LAS unsigned char* lds, const Gemm g, const Sched& S, const Epi& E) {
;     ...
;             PG8_LDA(At, 0, 1); PG8_STAGE(PG8_SB(0, 0), b2, voffB); PG8_STAGE(PG8_SB(0, 1), b2 + hstep, voffB); PG8_STAGE(PG8_SA(0, 0), a2, voffA);
;             PG8_WAIT_V(8); PG8_WAIT_L(0); PG8_BAR; PG8_MMA(1, 0, At, B0); PG8_MMA(1, 1, At, B1); PG8_BAR; PG8_SCHED;
;             PG8_LDB(B0, 1, 0); PG8_LDB(B1, 1, 1); PG8_SCHED; PG8_LDA(At, 1, 0); PG8_STAGE(PG8_SA(0, 1), a2 + hstep, voffA);
	s_add_i32 s24, s76, s51
	v_lshl_add_u64 v[148:149], s[42:43], 0, v[132:133]
	s_mov_b32 m0, s24
	ds_read_b128 v[188:191], v152 offset:16384
	ds_read_b128 v[206:209], v152 offset:17408
	ds_read_b128 v[210:213], v152 offset:18432
	ds_read_b128 v[214:217], v152 offset:19456
	ds_read_b128 v[218:221], v152 offset:20480
	ds_read_b128 v[222:225], v152 offset:21504
	ds_read_b128 v[226:229], v152 offset:22528
	ds_read_b128 v[230:233], v152 offset:23552
	global_load_lds_dwordx4 v[148:149], off
	s_add_i32 m0, s24, 0x2000
	s_add_u32 s24, s42, 0x40000
	v_lshl_add_u64 v[234:235], s[42:43], 0, v[136:137]
	s_addc_u32 s25, s43, 0
	s_add_i32 s72, s72, s51
	global_load_lds_dwordx4 v[234:235], off
	v_lshl_add_u64 v[236:237], s[24:25], 0, v[132:133]
	s_mov_b32 m0, s72
	s_nop 0
	global_load_lds_dwordx4 v[236:237], off
	v_lshl_add_u64 v[236:237], s[24:25], 0, v[136:137]
	s_add_i32 m0, s72, 0x2000
	s_nop 0
	global_load_lds_dwordx4 v[236:237], off
	v_lshl_add_u64 v[236:237], s[46:47], 0, v[130:131]
	s_mov_b32 m0, s23
	s_nop 0
	global_load_lds_dwordx4 v[236:237], off
	v_lshl_add_u64 v[236:237], s[46:47], 0, v[134:135]
	s_mov_b32 m0, s56
	s_nop 0
	global_load_lds_dwordx4 v[236:237], off
	s_waitcnt vmcnt(8)
	s_waitcnt lgkmcnt(0)
	s_barrier
	s_setprio 1
	s_waitcnt lgkmcnt(0)
	v_mfma_f32_16x16x32_bf16 v[62:65], v[144:147], v[188:191], v[62:65]
	v_mfma_f32_16x16x32_bf16 v[62:65], v[160:163], v[206:209], v[62:65]
	v_mfma_f32_16x16x32_bf16 v[58:61], v[168:171], v[206:209], v[58:61]
	v_mfma_f32_16x16x32_bf16 v[58:61], v[164:167], v[188:191], v[58:61]
	v_mfma_f32_16x16x32_bf16 v[42:45], v[164:167], v[210:213], v[42:45]
	v_mfma_f32_16x16x32_bf16 v[42:45], v[168:171], v[214:217], v[42:45]
	v_mfma_f32_16x16x32_bf16 v[46:49], v[160:163], v[214:217], v[46:49]
	v_mfma_f32_16x16x32_bf16 v[46:49], v[144:147], v[210:213], v[46:49]
	v_mfma_f32_16x16x32_bf16 v[30:33], v[144:147], v[218:221], v[30:33]
	v_mfma_f32_16x16x32_bf16 v[30:33], v[160:163], v[222:225], v[30:33]
	v_mfma_f32_16x16x32_bf16 v[26:29], v[168:171], v[222:225], v[26:29]
	v_mfma_f32_16x16x32_bf16 v[26:29], v[164:167], v[218:221], v[26:29]
	v_mfma_f32_16x16x32_bf16 v[10:13], v[164:167], v[226:229], v[10:13]
	v_mfma_f32_16x16x32_bf16 v[10:13], v[168:171], v[230:233], v[10:13]
	v_mfma_f32_16x16x32_bf16 v[14:17], v[160:163], v[230:233], v[14:17]
	v_mfma_f32_16x16x32_bf16 v[14:17], v[144:147], v[226:229], v[14:17]
	s_setprio 0
	s_setprio 1
	v_mfma_f32_16x16x32_bf16 v[54:57], v[172:175], v[188:191], v[54:57]
	v_mfma_f32_16x16x32_bf16 v[54:57], v[176:179], v[206:209], v[54:57]
	v_mfma_f32_16x16x32_bf16 v[50:53], v[184:187], v[206:209], v[50:53]
	v_mfma_f32_16x16x32_bf16 v[50:53], v[180:183], v[188:191], v[50:53]
	v_mfma_f32_16x16x32_bf16 v[34:37], v[180:183], v[210:213], v[34:37]
	v_mfma_f32_16x16x32_bf16 v[34:37], v[184:187], v[214:217], v[34:37]
	v_mfma_f32_16x16x32_bf16 v[38:41], v[176:179], v[214:217], v[38:41]
	v_mfma_f32_16x16x32_bf16 v[38:41], v[172:175], v[210:213], v[38:41]
	v_mfma_f32_16x16x32_bf16 v[22:25], v[172:175], v[218:221], v[22:25]
	v_mfma_f32_16x16x32_bf16 v[22:25], v[176:179], v[222:225], v[22:25]
	v_mfma_f32_16x16x32_bf16 v[18:21], v[184:187], v[222:225], v[18:21]
	v_mfma_f32_16x16x32_bf16 v[18:21], v[180:183], v[218:221], v[18:21]
	v_mfma_f32_16x16x32_bf16 v[2:5], v[180:183], v[226:229], v[2:5]
	v_mfma_f32_16x16x32_bf16 v[2:5], v[184:187], v[230:233], v[2:5]
	v_mfma_f32_16x16x32_bf16 v[6:9], v[176:179], v[230:233], v[6:9]
	v_mfma_f32_16x16x32_bf16 v[6:9], v[172:175], v[226:229], v[6:9]
	s_setprio 0
	s_barrier
	s_add_i32 s72, 0, 0x18000
	v_add_u32_e32 v153, s72, v150
	s_add_i32 s73, 0, 0x1c000
	ds_read_b128 v[144:147], v153
	ds_read_b128 v[160:163], v153 offset:1024
	ds_read_b128 v[164:167], v153 offset:2048
	ds_read_b128 v[168:171], v153 offset:3072
	v_add_u32_e32 v153, s73, v150
	ds_read_b128 v[172:175], v153
	ds_read_b128 v[176:179], v153 offset:1024
	ds_read_b128 v[180:183], v153 offset:2048
	ds_read_b128 v[184:187], v153 offset:3072
	s_add_u32 s24, s46, 0x40000
	s_addc_u32 s25, s47, 0
	s_mov_b32 m0, s57
	v_lshl_add_u64 v[236:237], s[24:25], 0, v[130:131]
	ds_read_b128 v[188:191], v152 offset:32768
	ds_read_b128 v[206:209], v152 offset:33792
	ds_read_b128 v[210:213], v152 offset:34816
	ds_read_b128 v[214:217], v152 offset:35840
	ds_read_b128 v[218:221], v152 offset:36864
	ds_read_b128 v[222:225], v152 offset:37888
	ds_read_b128 v[226:229], v152 offset:38912
	ds_read_b128 v[230:233], v152 offset:39936
	global_load_lds_dwordx4 v[236:237], off
	v_lshl_add_u64 v[236:237], s[24:25], 0, v[134:135]
	s_mov_b32 m0, s58
	s_nop 0
	global_load_lds_dwordx4 v[236:237], off
	s_waitcnt vmcnt(8)
	s_waitcnt lgkmcnt(0)
	s_barrier
; #define PG8_STAGE(bufoff, gbase, voff) do { _Pragma("unroll") for (int _i = 0; _i < 2; ++_i) \
;         __builtin_amdgcn_global_load_lds((const unsigned*)((const char*)(gbase) + (voff)[_i]), (PG8_LAS unsigned*)(lds + (bufoff) + ldsw + _i * 8192), 16, 0, 0); } while (0)
; #define PG8_LDA(dst, b, h) do { _Pragma("unroll") for (int m = 0; m < 4; ++m) _Pragma("unroll") for (int k = 0; k < 2; ++k) dst[m][k] = *(const PG8_LAS bf16x8*)(lds + PG8_SA(b, h) + aoff + m * 2048 + k * 1024); } while (0)
; #define PG8_MMA(ai, bj, At, Bt) do { __builtin_amdgcn_s_setprio(1); _Pragma("unroll") for (int m = 0; m < 4; ++m) _Pragma("unroll") for (int n = 0; n < 2; ++n) _Pragma("unroll") for (int k = 0; k < 2; ++k) \
;         acc[ai][bj][m][n] = __builtin_amdgcn_mfma_f32_16x16x32_bf16(Bt[n][k], At[m][k], acc[ai][bj][m][n], 0, 0, 0); __builtin_amdgcn_s_setprio(0); } while (0)
; #define PG8_WAIT_V(n) asm volatile("s_waitcnt vmcnt(" #n ")" ::: "memory")
; #define PG8_WAIT_L(n) asm volatile("s_waitcnt lgkmcnt(" #n ")" ::: "memory")
; #define PG8_BAR __builtin_amdgcn_s_barrier()
; #define PG8_SCHED __builtin_amdgcn_sched_barrier(0)
; template <class Epi, class Sched, bool ALIGN_EPI = false, bool SP2 = false>
; __device__ __forceinline__ void gemm_phase(PG8_LAS unsigned char* lds, const Gemm g, const Sched& S, const Epi& E) {
;     ...
;             PG8_WAIT_V(8); PG8_WAIT_L(0); PG8_BAR; PG8_MMA(0, 0, At, B0); PG8_MMA(0, 1, At, B1); PG8_BAR; PG8_SCHED;
;             PG8_LDA(At, 1, 1); PG8_STAGE(PG8_SB(1, 0), b3, voffB); PG8_STAGE(PG8_SB(1, 1), b3 + hstep, voffB); PG8_STAGE(PG8_SA(1, 0), a3, voffA);
;             PG8_WAIT_V(8); PG8_WAIT_L(0); PG8_BAR; PG8_MMA(1, 0, At, B0); PG8_MMA(1, 1, At, B1); PG8_BAR; PG8_SCHED;
	s_setprio 1
	s_waitcnt lgkmcnt(0)
	v_mfma_f32_16x16x32_bf16 v[126:129], v[144:147], v[188:191], v[126:129]
	v_mfma_f32_16x16x32_bf16 v[126:129], v[160:163], v[206:209], v[126:129]
	v_mfma_f32_16x16x32_bf16 v[122:125], v[168:171], v[206:209], v[122:125]
	v_mfma_f32_16x16x32_bf16 v[122:125], v[164:167], v[188:191], v[122:125]
	v_mfma_f32_16x16x32_bf16 v[106:109], v[164:167], v[210:213], v[106:109]
	v_mfma_f32_16x16x32_bf16 v[106:109], v[168:171], v[214:217], v[106:109]
	v_mfma_f32_16x16x32_bf16 v[110:113], v[160:163], v[214:217], v[110:113]
	v_mfma_f32_16x16x32_bf16 v[110:113], v[144:147], v[210:213], v[110:113]
	v_mfma_f32_16x16x32_bf16 v[94:97], v[144:147], v[218:221], v[94:97]
	v_mfma_f32_16x16x32_bf16 v[94:97], v[160:163], v[222:225], v[94:97]
	v_mfma_f32_16x16x32_bf16 v[90:93], v[168:171], v[222:225], v[90:93]
	v_mfma_f32_16x16x32_bf16 v[90:93], v[164:167], v[218:221], v[90:93]
	v_mfma_f32_16x16x32_bf16 v[74:77], v[164:167], v[226:229], v[74:77]
	v_mfma_f32_16x16x32_bf16 v[74:77], v[168:171], v[230:233], v[74:77]
	v_mfma_f32_16x16x32_bf16 v[78:81], v[160:163], v[230:233], v[78:81]
	v_mfma_f32_16x16x32_bf16 v[78:81], v[144:147], v[226:229], v[78:81]
	s_setprio 0
	s_setprio 1
	v_mfma_f32_16x16x32_bf16 v[118:121], v[172:175], v[188:191], v[118:121]
	v_mfma_f32_16x16x32_bf16 v[118:121], v[176:179], v[206:209], v[118:121]
	v_mfma_f32_16x16x32_bf16 v[114:117], v[184:187], v[206:209], v[114:117]
	v_mfma_f32_16x16x32_bf16 v[114:117], v[180:183], v[188:191], v[114:117]
	v_mfma_f32_16x16x32_bf16 v[98:101], v[180:183], v[210:213], v[98:101]
	v_mfma_f32_16x16x32_bf16 v[98:101], v[184:187], v[214:217], v[98:101]
	v_mfma_f32_16x16x32_bf16 v[102:105], v[176:179], v[214:217], v[102:105]
	v_mfma_f32_16x16x32_bf16 v[102:105], v[172:175], v[210:213], v[102:105]
	v_mfma_f32_16x16x32_bf16 v[86:89], v[172:175], v[218:221], v[86:89]
	v_mfma_f32_16x16x32_bf16 v[86:89], v[176:179], v[222:225], v[86:89]
	v_mfma_f32_16x16x32_bf16 v[82:85], v[184:187], v[222:225], v[82:85]
	v_mfma_f32_16x16x32_bf16 v[82:85], v[180:183], v[218:221], v[82:85]
	v_mfma_f32_16x16x32_bf16 v[66:69], v[180:183], v[226:229], v[66:69]
	v_mfma_f32_16x16x32_bf16 v[66:69], v[184:187], v[230:233], v[66:69]
	v_mfma_f32_16x16x32_bf16 v[70:73], v[176:179], v[230:233], v[70:73]
	v_mfma_f32_16x16x32_bf16 v[70:73], v[172:175], v[226:229], v[70:73]
	s_setprio 0
	s_barrier
	s_add_i32 s24, s72, s51
	v_lshl_add_u64 v[148:149], v[148:149], 0, s[38:39]
	s_mov_b32 m0, s24
	ds_read_b128 v[188:191], v152 offset:49152
	ds_read_b128 v[206:209], v152 offset:50176
	ds_read_b128 v[210:213], v152 offset:51200
	ds_read_b128 v[214:217], v152 offset:52224
	ds_read_b128 v[218:221], v152 offset:53248
	ds_read_b128 v[222:225], v152 offset:54272
	ds_read_b128 v[226:229], v152 offset:55296
	ds_read_b128 v[230:233], v152 offset:56320
	global_load_lds_dwordx4 v[148:149], off
	s_add_i32 m0, s24, 0x2000
	s_add_u32 s24, s42, 0x40080
	v_lshl_add_u64 v[148:149], v[234:235], 0, s[38:39]
	s_addc_u32 s25, s43, 0
	s_add_i32 s42, s73, s51
	global_load_lds_dwordx4 v[148:149], off
	v_lshl_add_u64 v[148:149], s[24:25], 0, v[132:133]
	s_mov_b32 m0, s42
	s_nop 0
	global_load_lds_dwordx4 v[148:149], off
	v_lshl_add_u64 v[148:149], s[24:25], 0, v[136:137]
	s_add_i32 m0, s42, 0x2000
	s_nop 0
	global_load_lds_dwordx4 v[148:149], off
	v_lshl_add_u64 v[148:149], s[26:27], 0, v[130:131]
	s_mov_b32 m0, s64
	s_nop 0
	global_load_lds_dwordx4 v[148:149], off
	v_lshl_add_u64 v[148:149], s[26:27], 0, v[134:135]
	s_mov_b32 m0, s65
	s_nop 0
	global_load_lds_dwordx4 v[148:149], off
	s_waitcnt vmcnt(8)
	s_waitcnt lgkmcnt(0)
	s_barrier
	s_setprio 1
	s_waitcnt lgkmcnt(0)
	v_mfma_f32_16x16x32_bf16 v[62:65], v[144:147], v[188:191], v[62:65]
	v_mfma_f32_16x16x32_bf16 v[62:65], v[160:163], v[206:209], v[62:65]
	v_mfma_f32_16x16x32_bf16 v[58:61], v[168:171], v[206:209], v[58:61]
	v_mfma_f32_16x16x32_bf16 v[58:61], v[164:167], v[188:191], v[58:61]
	v_mfma_f32_16x16x32_bf16 v[42:45], v[164:167], v[210:213], v[42:45]
	v_mfma_f32_16x16x32_bf16 v[42:45], v[168:171], v[214:217], v[42:45]
	v_mfma_f32_16x16x32_bf16 v[46:49], v[160:163], v[214:217], v[46:49]
	v_mfma_f32_16x16x32_bf16 v[46:49], v[144:147], v[210:213], v[46:49]
	v_mfma_f32_16x16x32_bf16 v[30:33], v[144:147], v[218:221], v[30:33]
	v_mfma_f32_16x16x32_bf16 v[30:33], v[160:163], v[222:225], v[30:33]
	v_mfma_f32_16x16x32_bf16 v[26:29], v[168:171], v[222:225], v[26:29]
	v_mfma_f32_16x16x32_bf16 v[26:29], v[164:167], v[218:221], v[26:29]
	v_mfma_f32_16x16x32_bf16 v[10:13], v[164:167], v[226:229], v[10:13]
	v_mfma_f32_16x16x32_bf16 v[10:13], v[168:171], v[230:233], v[10:13]
	v_mfma_f32_16x16x32_bf16 v[14:17], v[160:163], v[230:233], v[14:17]
	v_mfma_f32_16x16x32_bf16 v[14:17], v[144:147], v[226:229], v[14:17]
	s_setprio 0
	s_setprio 1
	v_mfma_f32_16x16x32_bf16 v[54:57], v[172:175], v[188:191], v[54:57]
	v_mfma_f32_16x16x32_bf16 v[54:57], v[176:179], v[206:209], v[54:57]
	v_mfma_f32_16x16x32_bf16 v[50:53], v[184:187], v[206:209], v[50:53]
	v_mfma_f32_16x16x32_bf16 v[50:53], v[180:183], v[188:191], v[50:53]
	v_mfma_f32_16x16x32_bf16 v[34:37], v[180:183], v[210:213], v[34:37]
	v_mfma_f32_16x16x32_bf16 v[34:37], v[184:187], v[214:217], v[34:37]
	v_mfma_f32_16x16x32_bf16 v[38:41], v[176:179], v[214:217], v[38:41]
	v_mfma_f32_16x16x32_bf16 v[38:41], v[172:175], v[210:213], v[38:41]
	v_mfma_f32_16x16x32_bf16 v[22:25], v[172:175], v[218:221], v[22:25]
	v_mfma_f32_16x16x32_bf16 v[22:25], v[176:179], v[222:225], v[22:25]
	v_mfma_f32_16x16x32_bf16 v[18:21], v[184:187], v[222:225], v[18:21]
	v_mfma_f32_16x16x32_bf16 v[18:21], v[180:183], v[218:221], v[18:21]
	v_mfma_f32_16x16x32_bf16 v[2:5], v[180:183], v[226:229], v[2:5]
	v_mfma_f32_16x16x32_bf16 v[2:5], v[184:187], v[230:233], v[2:5]
	v_mfma_f32_16x16x32_bf16 v[6:9], v[176:179], v[230:233], v[6:9]
	v_mfma_f32_16x16x32_bf16 v[6:9], v[172:175], v[226:229], v[6:9]
	s_setprio 0
	s_barrier
	s_add_i32 s71, s71, 2
	s_add_u32 s69, s69, 0x100
	s_addc_u32 s70, s70, 0
	s_cmp_gt_u32 s71, 13
	s_mov_b64 s[24:25], s[2:3]
	s_cbranch_scc0 .LBB0_238
	s_and_b64 vcc, exec, s[6:7]
	s_cbranch_vccz .LBB0_241
	s_barrier

; #define PG8_STAGE(bufoff, gbase, voff) do { _Pragma("unroll") for (int _i = 0; _i < 2; ++_i) \
;         __builtin_amdgcn_global_load_lds((const unsigned*)((const char*)(gbase) + (voff)[_i]), (PG8_LAS unsigned*)(lds + (bufoff) + ldsw + _i * 8192), 16, 0, 0); } while (0)
; #define PG8_LDA(dst, b, h) do { _Pragma("unroll") for (int m = 0; m < 4; ++m) _Pragma("unroll") for (int k = 0; k < 2; ++k) dst[m][k] = *(const PG8_LAS bf16x8*)(lds + PG8_SA(b, h) + aoff + m * 2048 + k * 1024); } while (0)
; #define PG8_LDB(dst, b, h) do { _Pragma("unroll") for (int n = 0; n < 2; ++n) _Pragma("unroll") for (int k = 0; k < 2; ++k) dst[n][k] = *(const PG8_LAS bf16x8*)(lds + PG8_SB(b, h) + boff + n * 2048 + k * 1024); } while (0)
; #define PG8_MMA(ai, bj, At, Bt) do { __builtin_amdgcn_s_setprio(1); _Pragma("unroll") for (int m = 0; m < 4; ++m) _Pragma("unroll") for (int n = 0; n < 2; ++n) _Pragma("unroll") for (int k = 0; k < 2; ++k) \
;         acc[ai][bj][m][n] = __builtin_amdgcn_mfma_f32_16x16x32_bf16(Bt[n][k], At[m][k], acc[ai][bj][m][n], 0, 0, 0); __builtin_amdgcn_s_setprio(0); } while (0)
; #define PG8_WAIT_V(n) asm volatile("s_waitcnt vmcnt(" #n ")" ::: "memory")
; #define PG8_WAIT_L(n) asm volatile("s_waitcnt lgkmcnt(" #n ")" ::: "memory")
; template <class Epi, class Sched, bool ALIGN_EPI = false, bool SP2 = false>
; __device__ __forceinline__ void gemm_phase(PG8_LAS unsigned char* lds, const Gemm g, const Sched& S, const Epi& E) {
;     ...
;             const bool last = (t == nt - 2);
;             const char* a1 = cA + (size_t)(t + 1) * kstepA;
;             const char* a2 = last ? nA : cA + (size_t)(t + 2) * kstepA; const char* b2 = last ? nB : cB + (size_t)(t + 2) * kstep;
;             const char* a3 = a2 + kstepA; const char* b3 = b2 + kstep;
;             if (last && has_next) S.a_ready(nxt);
;             if constexpr (SP2) {
;             PG8_LDB(B0, 0, 0); PG8_LDB(B1, 0, 1); PG8_SCHED; PG8_LDA(At, 0, 0); PG8_STAGE(PG8_SA(1, 1), a1 + hstep, voffA);
;             PG8_WAIT_V(8); PG8_WAIT_L(0); PG8_BAR; PG8_MMA(0, 0, At, B0); PG8_MMA(0, 1, At, B1); PG8_BAR; PG8_SCHED;
;     ...
; #pragma unroll
;         for (int a = 0; a < 2; ++a)
; #pragma unroll
;             for (int b = 0; b < 2; ++b)
; #pragma unroll
;                 for (int m = 0; m < 4; ++m)
; #pragma unroll
;                     for (int n = 0; n < 2; ++n) acc[a][b][m][n] = (f32x4){0.f, 0.f, 0.f, 0.f};
.LBB0_309:
	s_add_u32 s47, s24, 0x100
	s_addc_u32 s48, s25, 0
	s_add_u32 s2, s26, 0x4000
	v_mov_b64_e32 v[2:3], 0
	v_mov_b64_e32 v[4:5], 0
	v_mov_b64_e32 v[6:7], 0
	v_mov_b64_e32 v[8:9], 0
	v_mov_b64_e32 v[10:11], 0
	v_mov_b64_e32 v[12:13], 0
	v_mov_b64_e32 v[14:15], 0
	v_mov_b64_e32 v[16:17], 0
	v_mov_b64_e32 v[18:19], 0
	v_mov_b64_e32 v[20:21], 0
	v_mov_b64_e32 v[22:23], 0
	v_mov_b64_e32 v[24:25], 0
	v_mov_b64_e32 v[26:27], 0
	v_mov_b64_e32 v[28:29], 0
	v_mov_b64_e32 v[30:31], 0
	v_mov_b64_e32 v[32:33], 0
	v_mov_b64_e32 v[34:35], 0
	v_mov_b64_e32 v[36:37], 0
	v_mov_b64_e32 v[38:39], 0
	v_mov_b64_e32 v[40:41], 0
	v_mov_b64_e32 v[42:43], 0
	v_mov_b64_e32 v[44:45], 0
	v_mov_b64_e32 v[46:47], 0
	v_mov_b64_e32 v[48:49], 0
	v_mov_b64_e32 v[50:51], 0
	v_mov_b64_e32 v[52:53], 0
	v_mov_b64_e32 v[54:55], 0
	v_mov_b64_e32 v[56:57], 0
	v_mov_b64_e32 v[58:59], 0
	v_mov_b64_e32 v[60:61], 0
	v_mov_b64_e32 v[62:63], 0
	v_mov_b64_e32 v[64:65], 0
	v_mov_b64_e32 v[66:67], 0
	v_mov_b64_e32 v[68:69], 0
	v_mov_b64_e32 v[70:71], 0
	v_mov_b64_e32 v[72:73], 0
	v_mov_b64_e32 v[74:75], 0
	v_mov_b64_e32 v[76:77], 0
	v_mov_b64_e32 v[78:79], 0
	v_mov_b64_e32 v[80:81], 0
	v_mov_b64_e32 v[82:83], 0
	v_mov_b64_e32 v[84:85], 0
	v_mov_b64_e32 v[86:87], 0
	v_mov_b64_e32 v[88:89], 0
	v_mov_b64_e32 v[90:91], 0
	v_mov_b64_e32 v[92:93], 0
	v_mov_b64_e32 v[94:95], 0
	v_mov_b64_e32 v[96:97], 0
	v_mov_b64_e32 v[98:99], 0
	v_mov_b64_e32 v[100:101], 0
	v_mov_b64_e32 v[102:103], 0
	v_mov_b64_e32 v[104:105], 0
	v_mov_b64_e32 v[106:107], 0
	v_mov_b64_e32 v[108:109], 0
	v_mov_b64_e32 v[110:111], 0
	v_mov_b64_e32 v[112:113], 0
	v_mov_b64_e32 v[114:115], 0
	v_mov_b64_e32 v[116:117], 0
	v_mov_b64_e32 v[118:119], 0
	v_mov_b64_e32 v[120:121], 0
	v_mov_b64_e32 v[122:123], 0
	v_mov_b64_e32 v[124:125], 0
	v_mov_b64_e32 v[126:127], 0
	v_mov_b64_e32 v[128:129], 0
	s_addc_u32 s3, s27, 0
	s_mov_b32 s24, 0
.LBB0_310:
	s_add_i32 s49, s24, 2
	s_add_u32 s25, s2, 0x4000
	s_addc_u32 s26, s3, 0
	s_cmp_eq_u32 s59, s24
	s_cselect_b32 s27, s9, s26
	s_cselect_b32 s26, s8, s25
	s_cselect_b32 s66, s44, s47
	s_cselect_b32 s67, s45, s48
	s_add_u32 s24, s26, 0x4000
	s_addc_u32 s25, s27, 0
	s_add_i32 s65, 0, 0x14000
	v_add_u32_e32 v142, s76, v187
	v_add_u32_e32 v167, s65, v187
	ds_read_b128 v[130:133], v142
	ds_read_b128 v[134:137], v142 offset:1024
	ds_read_b128 v[138:141], v142 offset:2048
	ds_read_b128 v[142:145], v142 offset:3072
	ds_read_b128 v[146:149], v167
	ds_read_b128 v[150:153], v167 offset:1024
	ds_read_b128 v[206:209], v167 offset:2048
	ds_read_b128 v[210:213], v167 offset:3072
	v_lshl_add_u64 v[184:185], s[2:3], 0, v[182:183]
	s_add_i32 m0, s51, 0xc000
	ds_read_b128 v[214:217], v188
	ds_read_b128 v[218:221], v188 offset:1024
	ds_read_b128 v[222:225], v188 offset:2048
	ds_read_b128 v[226:229], v188 offset:3072
	ds_read_b128 v[230:233], v188 offset:4096
	ds_read_b128 v[234:237], v188 offset:5120
	ds_read_b128 v[238:241], v188 offset:6144
	ds_read_b128 v[242:245], v188 offset:7168
	global_load_lds_dwordx4 v[184:185], off
	v_lshl_add_u64 v[184:185], s[2:3], 0, v[180:181]
	s_add_i32 m0, s51, 0xe000
	s_nop 0
	global_load_lds_dwordx4 v[184:185], off
	s_waitcnt vmcnt(8)
	s_waitcnt lgkmcnt(0)
	s_barrier
	s_setprio 1
	s_waitcnt lgkmcnt(0)
	v_mfma_f32_16x16x32_bf16 v[126:129], v[130:133], v[214:217], v[126:129]
	v_mfma_f32_16x16x32_bf16 v[126:129], v[134:137], v[218:221], v[126:129]
	v_mfma_f32_16x16x32_bf16 v[122:125], v[142:145], v[218:221], v[122:125]
	v_mfma_f32_16x16x32_bf16 v[122:125], v[138:141], v[214:217], v[122:125]
	v_mfma_f32_16x16x32_bf16 v[106:109], v[138:141], v[222:225], v[106:109]
	v_mfma_f32_16x16x32_bf16 v[106:109], v[142:145], v[226:229], v[106:109]
	v_mfma_f32_16x16x32_bf16 v[110:113], v[134:137], v[226:229], v[110:113]
	v_mfma_f32_16x16x32_bf16 v[110:113], v[130:133], v[222:225], v[110:113]
	v_mfma_f32_16x16x32_bf16 v[94:97], v[130:133], v[230:233], v[94:97]
	v_mfma_f32_16x16x32_bf16 v[94:97], v[134:137], v[234:237], v[94:97]
	v_mfma_f32_16x16x32_bf16 v[90:93], v[142:145], v[234:237], v[90:93]
	v_mfma_f32_16x16x32_bf16 v[90:93], v[138:141], v[230:233], v[90:93]
	v_mfma_f32_16x16x32_bf16 v[74:77], v[138:141], v[238:241], v[74:77]
	v_mfma_f32_16x16x32_bf16 v[74:77], v[142:145], v[242:245], v[74:77]
	v_mfma_f32_16x16x32_bf16 v[78:81], v[134:137], v[242:245], v[78:81]
	v_mfma_f32_16x16x32_bf16 v[78:81], v[130:133], v[238:241], v[78:81]
	s_setprio 0
	s_setprio 1
	v_mfma_f32_16x16x32_bf16 v[118:121], v[146:149], v[214:217], v[118:121]
	v_mfma_f32_16x16x32_bf16 v[118:121], v[150:153], v[218:221], v[118:121]
	v_mfma_f32_16x16x32_bf16 v[114:117], v[210:213], v[218:221], v[114:117]
	v_mfma_f32_16x16x32_bf16 v[114:117], v[206:209], v[214:217], v[114:117]
	v_mfma_f32_16x16x32_bf16 v[98:101], v[206:209], v[222:225], v[98:101]
	v_mfma_f32_16x16x32_bf16 v[98:101], v[210:213], v[226:229], v[98:101]
	v_mfma_f32_16x16x32_bf16 v[102:105], v[150:153], v[226:229], v[102:105]
	v_mfma_f32_16x16x32_bf16 v[102:105], v[146:149], v[222:225], v[102:105]
	v_mfma_f32_16x16x32_bf16 v[86:89], v[146:149], v[230:233], v[86:89]
	v_mfma_f32_16x16x32_bf16 v[86:89], v[150:153], v[234:237], v[86:89]
	v_mfma_f32_16x16x32_bf16 v[82:85], v[210:213], v[234:237], v[82:85]
	v_mfma_f32_16x16x32_bf16 v[82:85], v[206:209], v[230:233], v[82:85]
	v_mfma_f32_16x16x32_bf16 v[66:69], v[206:209], v[238:241], v[66:69]
	v_mfma_f32_16x16x32_bf16 v[66:69], v[210:213], v[242:245], v[66:69]
	v_mfma_f32_16x16x32_bf16 v[70:73], v[150:153], v[242:245], v[70:73]
	v_mfma_f32_16x16x32_bf16 v[70:73], v[146:149], v[238:241], v[70:73]
	s_setprio 0
	s_barrier
; #define PG8_STAGE(bufoff, gbase, voff) do { _Pragma("unroll") for (int _i = 0; _i < 2; ++_i) \
;         __builtin_amdgcn_global_load_lds((const unsigned*)((const char*)(gbase) + (voff)[_i]), (PG8_LAS unsigned*)(lds + (bufoff) + ldsw + _i * 8192), 16, 0, 0); } while (0)
; #define PG8_LDA(dst, b, h) do { _Pragma("unroll") for (int m = 0; m < 4; ++m) _Pragma("unroll") for (int k = 0; k < 2; ++k) dst[m][k] = *(const PG8_LAS bf16x8*)(lds + PG8_SA(b, h) + aoff + m * 2048 + k * 1024); } while (0)
; #define PG8_LDB(dst, b, h) do { _Pragma("unroll") for (int n = 0; n < 2; ++n) _Pragma("unroll") for (int k = 0; k < 2; ++k) dst[n][k] = *(const PG8_LAS bf16x8*)(lds + PG8_SB(b, h) + boff + n * 2048 + k * 1024); } while (0)
; #define PG8_MMA(ai, bj, At, Bt) do { __builtin_amdgcn_s_setprio(1); _Pragma("unroll") for (int m = 0; m < 4; ++m) _Pragma("unroll") for (int n = 0; n < 2; ++n) _Pragma("unroll") for (int k = 0; k < 2; ++k) \
;         acc[ai][bj][m][n] = __builtin_amdgcn_mfma_f32_16x16x32_bf16(Bt[n][k], At[m][k], acc[ai][bj][m][n], 0, 0, 0); __builtin_amdgcn_s_setprio(0); } while (0)
; #define PG8_WAIT_V(n) asm volatile("s_waitcnt vmcnt(" #n ")" ::: "memory")
; #define PG8_WAIT_L(n) asm volatile("s_waitcnt lgkmcnt(" #n ")" ::: "memory")
; #define PG8_BAR __builtin_amdgcn_s_barrier()
; #define PG8_SCHED __builtin_amdgcn_sched_barrier(0)
; template <class Epi, class Sched, bool ALIGN_EPI = false, bool SP2 = false>
; __device__ __forceinline__ void gemm_phase(PG8_LAS unsigned char* lds, const Gemm g, const Sched& S, const Epi& E) {
;     ...
;             PG8_LDA(At, 0, 1); PG8_STAGE(PG8_SB(0, 0), b2, voffB); PG8_STAGE(PG8_SB(0, 1), b2 + hstep, voffB); PG8_STAGE(PG8_SA(0, 0), a2, voffA);
;             PG8_WAIT_V(8); PG8_WAIT_L(0); PG8_BAR; PG8_MMA(1, 0, At, B0); PG8_MMA(1, 1, At, B1); PG8_BAR; PG8_SCHED;
;             PG8_LDB(B0, 1, 0); PG8_LDB(B1, 1, 1); PG8_SCHED; PG8_LDA(At, 1, 0); PG8_STAGE(PG8_SA(0, 1), a2 + hstep, voffA);
	s_add_i32 s68, s76, s50
	v_lshl_add_u64 v[184:185], s[66:67], 0, v[0:1]
	s_mov_b32 m0, s68
	ds_read_b128 v[214:217], v188 offset:16384
	ds_read_b128 v[218:221], v188 offset:17408
	ds_read_b128 v[222:225], v188 offset:18432
	ds_read_b128 v[226:229], v188 offset:19456
	ds_read_b128 v[230:233], v188 offset:20480
	ds_read_b128 v[234:237], v188 offset:21504
	ds_read_b128 v[238:241], v188 offset:22528
	ds_read_b128 v[242:245], v188 offset:23552
	global_load_lds_dwordx4 v[184:185], off
	s_add_i32 m0, s68, 0x2000
	v_lshl_add_u64 v[190:191], s[66:67], 0, v[164:165]
	s_add_u32 s66, s66, s12
	s_addc_u32 s67, s67, 0
	s_add_i32 s65, s65, s50
	global_load_lds_dwordx4 v[190:191], off
	v_lshl_add_u64 v[246:247], s[66:67], 0, v[0:1]
	s_mov_b32 m0, s65
	v_lshl_add_u64 v[248:249], s[66:67], 0, v[164:165]
	global_load_lds_dwordx4 v[246:247], off
	s_add_i32 m0, s65, 0x2000
	v_lshl_add_u64 v[250:251], s[26:27], 0, v[160:161]
	global_load_lds_dwordx4 v[248:249], off
	s_mov_b32 m0, s51
	s_nop 0
	global_load_lds_dwordx4 v[250:251], off
	v_lshl_add_u64 v[250:251], s[26:27], 0, v[162:163]
	s_mov_b32 m0, s52
	s_nop 0
	global_load_lds_dwordx4 v[250:251], off
	s_waitcnt vmcnt(8)
	s_waitcnt lgkmcnt(0)
	s_barrier
	s_setprio 1
	s_waitcnt lgkmcnt(0)
	v_mfma_f32_16x16x32_bf16 v[62:65], v[130:133], v[214:217], v[62:65]
	v_mfma_f32_16x16x32_bf16 v[62:65], v[134:137], v[218:221], v[62:65]
	v_mfma_f32_16x16x32_bf16 v[58:61], v[142:145], v[218:221], v[58:61]
	v_mfma_f32_16x16x32_bf16 v[58:61], v[138:141], v[214:217], v[58:61]
	v_mfma_f32_16x16x32_bf16 v[42:45], v[138:141], v[222:225], v[42:45]
	v_mfma_f32_16x16x32_bf16 v[42:45], v[142:145], v[226:229], v[42:45]
	v_mfma_f32_16x16x32_bf16 v[46:49], v[134:137], v[226:229], v[46:49]
	v_mfma_f32_16x16x32_bf16 v[46:49], v[130:133], v[222:225], v[46:49]
	v_mfma_f32_16x16x32_bf16 v[30:33], v[130:133], v[230:233], v[30:33]
	v_mfma_f32_16x16x32_bf16 v[30:33], v[134:137], v[234:237], v[30:33]
	v_mfma_f32_16x16x32_bf16 v[26:29], v[142:145], v[234:237], v[26:29]
	v_mfma_f32_16x16x32_bf16 v[26:29], v[138:141], v[230:233], v[26:29]
	v_mfma_f32_16x16x32_bf16 v[10:13], v[138:141], v[238:241], v[10:13]
	v_mfma_f32_16x16x32_bf16 v[10:13], v[142:145], v[242:245], v[10:13]
	v_mfma_f32_16x16x32_bf16 v[14:17], v[134:137], v[242:245], v[14:17]
	v_mfma_f32_16x16x32_bf16 v[14:17], v[130:133], v[238:241], v[14:17]
	s_setprio 0
	s_setprio 1
	v_mfma_f32_16x16x32_bf16 v[54:57], v[146:149], v[214:217], v[54:57]
	v_mfma_f32_16x16x32_bf16 v[54:57], v[150:153], v[218:221], v[54:57]
	v_mfma_f32_16x16x32_bf16 v[50:53], v[210:213], v[218:221], v[50:53]
	v_mfma_f32_16x16x32_bf16 v[50:53], v[206:209], v[214:217], v[50:53]
	v_mfma_f32_16x16x32_bf16 v[34:37], v[206:209], v[222:225], v[34:37]
	v_mfma_f32_16x16x32_bf16 v[34:37], v[210:213], v[226:229], v[34:37]
	v_mfma_f32_16x16x32_bf16 v[38:41], v[150:153], v[226:229], v[38:41]
	v_mfma_f32_16x16x32_bf16 v[38:41], v[146:149], v[222:225], v[38:41]
	v_mfma_f32_16x16x32_bf16 v[22:25], v[146:149], v[230:233], v[22:25]
	v_mfma_f32_16x16x32_bf16 v[22:25], v[150:153], v[234:237], v[22:25]
	v_mfma_f32_16x16x32_bf16 v[18:21], v[210:213], v[234:237], v[18:21]
	v_mfma_f32_16x16x32_bf16 v[18:21], v[206:209], v[230:233], v[18:21]
	v_mfma_f32_16x16x32_bf16 v[2:5], v[206:209], v[238:241], v[2:5]
	v_mfma_f32_16x16x32_bf16 v[2:5], v[210:213], v[242:245], v[2:5]
	v_mfma_f32_16x16x32_bf16 v[6:9], v[150:153], v[242:245], v[6:9]
	v_mfma_f32_16x16x32_bf16 v[6:9], v[146:149], v[238:241], v[6:9]
	s_setprio 0
	s_barrier
	s_add_i32 s65, 0, 0x18000
	s_add_i32 s66, 0, 0x1c000
	v_add_u32_e32 v142, s65, v187
	v_add_u32_e32 v167, s66, v187
	ds_read_b128 v[130:133], v142
	ds_read_b128 v[134:137], v142 offset:1024
	ds_read_b128 v[138:141], v142 offset:2048
	ds_read_b128 v[142:145], v142 offset:3072
	ds_read_b128 v[146:149], v167
	ds_read_b128 v[150:153], v167 offset:1024
	ds_read_b128 v[206:209], v167 offset:2048
	ds_read_b128 v[210:213], v167 offset:3072
	s_add_u32 s26, s26, s12
	s_addc_u32 s27, s27, 0
	s_mov_b32 m0, s53
	v_lshl_add_u64 v[250:251], s[26:27], 0, v[160:161]
	ds_read_b128 v[214:217], v188 offset:32768
	ds_read_b128 v[218:221], v188 offset:33792
	ds_read_b128 v[222:225], v188 offset:34816
	ds_read_b128 v[226:229], v188 offset:35840
	ds_read_b128 v[230:233], v188 offset:36864
	ds_read_b128 v[234:237], v188 offset:37888
	ds_read_b128 v[238:241], v188 offset:38912
	ds_read_b128 v[242:245], v188 offset:39936
	global_load_lds_dwordx4 v[250:251], off
	v_lshl_add_u64 v[250:251], s[26:27], 0, v[162:163]
	s_mov_b32 m0, s54
	s_nop 0
	global_load_lds_dwordx4 v[250:251], off
	s_waitcnt vmcnt(8)
	s_waitcnt lgkmcnt(0)
	s_barrier
; #define PG8_STAGE(bufoff, gbase, voff) do { _Pragma("unroll") for (int _i = 0; _i < 2; ++_i) \
;         __builtin_amdgcn_global_load_lds((const unsigned*)((const char*)(gbase) + (voff)[_i]), (PG8_LAS unsigned*)(lds + (bufoff) + ldsw + _i * 8192), 16, 0, 0); } while (0)
; #define PG8_LDA(dst, b, h) do { _Pragma("unroll") for (int m = 0; m < 4; ++m) _Pragma("unroll") for (int k = 0; k < 2; ++k) dst[m][k] = *(const PG8_LAS bf16x8*)(lds + PG8_SA(b, h) + aoff + m * 2048 + k * 1024); } while (0)
; #define PG8_MMA(ai, bj, At, Bt) do { __builtin_amdgcn_s_setprio(1); _Pragma("unroll") for (int m = 0; m < 4; ++m) _Pragma("unroll") for (int n = 0; n < 2; ++n) _Pragma("unroll") for (int k = 0; k < 2; ++k) \
;         acc[ai][bj][m][n] = __builtin_amdgcn_mfma_f32_16x16x32_bf16(Bt[n][k], At[m][k], acc[ai][bj][m][n], 0, 0, 0); __builtin_amdgcn_s_setprio(0); } while (0)
; #define PG8_WAIT_V(n) asm volatile("s_waitcnt vmcnt(" #n ")" ::: "memory")
; #define PG8_WAIT_L(n) asm volatile("s_waitcnt lgkmcnt(" #n ")" ::: "memory")
; #define PG8_BAR __builtin_amdgcn_s_barrier()
; #define PG8_SCHED __builtin_amdgcn_sched_barrier(0)
; template <class Epi, class Sched, bool ALIGN_EPI = false, bool SP2 = false>
; __device__ __forceinline__ void gemm_phase(PG8_LAS unsigned char* lds, const Gemm g, const Sched& S, const Epi& E) {
;     ...
;             PG8_WAIT_V(8); PG8_WAIT_L(0); PG8_BAR; PG8_MMA(0, 0, At, B0); PG8_MMA(0, 1, At, B1); PG8_BAR; PG8_SCHED;
;             PG8_LDA(At, 1, 1); PG8_STAGE(PG8_SB(1, 0), b3, voffB); PG8_STAGE(PG8_SB(1, 1), b3 + hstep, voffB); PG8_STAGE(PG8_SA(1, 0), a3, voffA);
;             PG8_WAIT_V(8); PG8_WAIT_L(0); PG8_BAR; PG8_MMA(1, 0, At, B0); PG8_MMA(1, 1, At, B1); PG8_BAR; PG8_SCHED;
	s_setprio 1
	s_waitcnt lgkmcnt(0)
	v_mfma_f32_16x16x32_bf16 v[126:129], v[130:133], v[214:217], v[126:129]
	v_mfma_f32_16x16x32_bf16 v[126:129], v[134:137], v[218:221], v[126:129]
	v_mfma_f32_16x16x32_bf16 v[122:125], v[142:145], v[218:221], v[122:125]
	v_mfma_f32_16x16x32_bf16 v[122:125], v[138:141], v[214:217], v[122:125]
	v_mfma_f32_16x16x32_bf16 v[106:109], v[138:141], v[222:225], v[106:109]
	v_mfma_f32_16x16x32_bf16 v[106:109], v[142:145], v[226:229], v[106:109]
	v_mfma_f32_16x16x32_bf16 v[110:113], v[134:137], v[226:229], v[110:113]
	v_mfma_f32_16x16x32_bf16 v[110:113], v[130:133], v[222:225], v[110:113]
	v_mfma_f32_16x16x32_bf16 v[94:97], v[130:133], v[230:233], v[94:97]
	v_mfma_f32_16x16x32_bf16 v[94:97], v[134:137], v[234:237], v[94:97]
	v_mfma_f32_16x16x32_bf16 v[90:93], v[142:145], v[234:237], v[90:93]
	v_mfma_f32_16x16x32_bf16 v[90:93], v[138:141], v[230:233], v[90:93]
	v_mfma_f32_16x16x32_bf16 v[74:77], v[138:141], v[238:241], v[74:77]
	v_mfma_f32_16x16x32_bf16 v[74:77], v[142:145], v[242:245], v[74:77]
	v_mfma_f32_16x16x32_bf16 v[78:81], v[134:137], v[242:245], v[78:81]
	v_mfma_f32_16x16x32_bf16 v[78:81], v[130:133], v[238:241], v[78:81]
	s_setprio 0
	s_setprio 1
	v_mfma_f32_16x16x32_bf16 v[118:121], v[146:149], v[214:217], v[118:121]
	v_mfma_f32_16x16x32_bf16 v[118:121], v[150:153], v[218:221], v[118:121]
	v_mfma_f32_16x16x32_bf16 v[114:117], v[210:213], v[218:221], v[114:117]
	v_mfma_f32_16x16x32_bf16 v[114:117], v[206:209], v[214:217], v[114:117]
	v_mfma_f32_16x16x32_bf16 v[98:101], v[206:209], v[222:225], v[98:101]
	v_mfma_f32_16x16x32_bf16 v[98:101], v[210:213], v[226:229], v[98:101]
	v_mfma_f32_16x16x32_bf16 v[102:105], v[150:153], v[226:229], v[102:105]
	v_mfma_f32_16x16x32_bf16 v[102:105], v[146:149], v[222:225], v[102:105]
	v_mfma_f32_16x16x32_bf16 v[86:89], v[146:149], v[230:233], v[86:89]
	v_mfma_f32_16x16x32_bf16 v[86:89], v[150:153], v[234:237], v[86:89]
	v_mfma_f32_16x16x32_bf16 v[82:85], v[210:213], v[234:237], v[82:85]
	v_mfma_f32_16x16x32_bf16 v[82:85], v[206:209], v[230:233], v[82:85]
	v_mfma_f32_16x16x32_bf16 v[66:69], v[206:209], v[238:241], v[66:69]
	v_mfma_f32_16x16x32_bf16 v[66:69], v[210:213], v[242:245], v[66:69]
	v_mfma_f32_16x16x32_bf16 v[70:73], v[150:153], v[242:245], v[70:73]
	v_mfma_f32_16x16x32_bf16 v[70:73], v[146:149], v[238:241], v[70:73]
	s_setprio 0
	s_barrier
	s_add_i32 s26, s65, s50
	v_lshl_add_u64 v[184:185], v[184:185], 0, s[38:39]
	s_mov_b32 m0, s26
	ds_read_b128 v[214:217], v188 offset:49152
	ds_read_b128 v[218:221], v188 offset:50176
	ds_read_b128 v[222:225], v188 offset:51200
	ds_read_b128 v[226:229], v188 offset:52224
	ds_read_b128 v[230:233], v188 offset:53248
	ds_read_b128 v[234:237], v188 offset:54272
	ds_read_b128 v[238:241], v188 offset:55296
	ds_read_b128 v[242:245], v188 offset:56320
	global_load_lds_dwordx4 v[184:185], off
	v_lshl_add_u64 v[184:185], v[190:191], 0, s[38:39]
	s_add_i32 m0, s26, 0x2000
	s_add_i32 s26, s66, s50
	global_load_lds_dwordx4 v[184:185], off
	v_lshl_add_u64 v[184:185], v[246:247], 0, s[38:39]
	s_mov_b32 m0, s26
	s_nop 0
	global_load_lds_dwordx4 v[184:185], off
	v_lshl_add_u64 v[184:185], v[248:249], 0, s[38:39]
	s_add_i32 m0, s26, 0x2000
	s_nop 0
	global_load_lds_dwordx4 v[184:185], off
	v_lshl_add_u64 v[184:185], s[24:25], 0, v[160:161]
	s_mov_b32 m0, s56
	s_nop 0
	global_load_lds_dwordx4 v[184:185], off
	v_lshl_add_u64 v[184:185], s[24:25], 0, v[162:163]
	s_mov_b32 m0, s57
	s_nop 0
	global_load_lds_dwordx4 v[184:185], off
	s_waitcnt vmcnt(8)
	s_waitcnt lgkmcnt(0)
	s_barrier
	s_setprio 1
	s_waitcnt lgkmcnt(0)
	v_mfma_f32_16x16x32_bf16 v[62:65], v[130:133], v[214:217], v[62:65]
	v_mfma_f32_16x16x32_bf16 v[62:65], v[134:137], v[218:221], v[62:65]
	v_mfma_f32_16x16x32_bf16 v[58:61], v[142:145], v[218:221], v[58:61]
	v_mfma_f32_16x16x32_bf16 v[58:61], v[138:141], v[214:217], v[58:61]
	v_mfma_f32_16x16x32_bf16 v[42:45], v[138:141], v[222:225], v[42:45]
	v_mfma_f32_16x16x32_bf16 v[42:45], v[142:145], v[226:229], v[42:45]
	v_mfma_f32_16x16x32_bf16 v[46:49], v[134:137], v[226:229], v[46:49]
	v_mfma_f32_16x16x32_bf16 v[46:49], v[130:133], v[222:225], v[46:49]
	v_mfma_f32_16x16x32_bf16 v[30:33], v[130:133], v[230:233], v[30:33]
	v_mfma_f32_16x16x32_bf16 v[30:33], v[134:137], v[234:237], v[30:33]
	v_mfma_f32_16x16x32_bf16 v[26:29], v[142:145], v[234:237], v[26:29]
	v_mfma_f32_16x16x32_bf16 v[26:29], v[138:141], v[230:233], v[26:29]
	v_mfma_f32_16x16x32_bf16 v[10:13], v[138:141], v[238:241], v[10:13]
	v_mfma_f32_16x16x32_bf16 v[10:13], v[142:145], v[242:245], v[10:13]
	v_mfma_f32_16x16x32_bf16 v[14:17], v[134:137], v[242:245], v[14:17]
	v_mfma_f32_16x16x32_bf16 v[14:17], v[130:133], v[238:241], v[14:17]
	s_setprio 0
	s_setprio 1
	v_mfma_f32_16x16x32_bf16 v[54:57], v[146:149], v[214:217], v[54:57]
	v_mfma_f32_16x16x32_bf16 v[54:57], v[150:153], v[218:221], v[54:57]
	v_mfma_f32_16x16x32_bf16 v[50:53], v[210:213], v[218:221], v[50:53]
	v_mfma_f32_16x16x32_bf16 v[50:53], v[206:209], v[214:217], v[50:53]
	v_mfma_f32_16x16x32_bf16 v[34:37], v[206:209], v[222:225], v[34:37]
	v_mfma_f32_16x16x32_bf16 v[34:37], v[210:213], v[226:229], v[34:37]
	v_mfma_f32_16x16x32_bf16 v[38:41], v[150:153], v[226:229], v[38:41]
	v_mfma_f32_16x16x32_bf16 v[38:41], v[146:149], v[222:225], v[38:41]
	v_mfma_f32_16x16x32_bf16 v[22:25], v[146:149], v[230:233], v[22:25]
	v_mfma_f32_16x16x32_bf16 v[22:25], v[150:153], v[234:237], v[22:25]
	v_mfma_f32_16x16x32_bf16 v[18:21], v[210:213], v[234:237], v[18:21]
	v_mfma_f32_16x16x32_bf16 v[18:21], v[206:209], v[230:233], v[18:21]
	v_mfma_f32_16x16x32_bf16 v[2:5], v[206:209], v[238:241], v[2:5]
	v_mfma_f32_16x16x32_bf16 v[2:5], v[210:213], v[242:245], v[2:5]
	v_mfma_f32_16x16x32_bf16 v[6:9], v[150:153], v[242:245], v[6:9]
	v_mfma_f32_16x16x32_bf16 v[6:9], v[146:149], v[238:241], v[6:9]
	s_setprio 0
	s_barrier
	s_add_u32 s47, s47, 0x100
	s_addc_u32 s48, s48, 0
	s_add_u32 s2, s2, 0x8000
	s_addc_u32 s3, s3, 0
	s_cmp_ge_u32 s49, s55
	s_mov_b32 s24, s49
	s_cbranch_scc0 .LBB0_310
	s_and_b64 vcc, exec, s[42:43]
	s_cbranch_vccz .LBB0_313
	s_barrier

; #define PG8_STAGE(bufoff, gbase, voff) do { _Pragma("unroll") for (int _i = 0; _i < 2; ++_i) \
;         __builtin_amdgcn_global_load_lds((const unsigned*)((const char*)(gbase) + (voff)[_i]), (PG8_LAS unsigned*)(lds + (bufoff) + ldsw + _i * 8192), 16, 0, 0); } while (0)
; #define PG8_LDA(dst, b, h) do { _Pragma("unroll") for (int m = 0; m < 4; ++m) _Pragma("unroll") for (int k = 0; k < 2; ++k) dst[m][k] = *(const PG8_LAS bf16x8*)(lds + PG8_SA(b, h) + aoff + m * 2048 + k * 1024); } while (0)
; #define PG8_LDB(dst, b, h) do { _Pragma("unroll") for (int n = 0; n < 2; ++n) _Pragma("unroll") for (int k = 0; k < 2; ++k) dst[n][k] = *(const PG8_LAS bf16x8*)(lds + PG8_SB(b, h) + boff + n * 2048 + k * 1024); } while (0)
; #define PG8_WAIT_V(n) asm volatile("s_waitcnt vmcnt(" #n ")" ::: "memory")
; #define PG8_WAIT_L(n) asm volatile("s_waitcnt lgkmcnt(" #n ")" ::: "memory")
; #define PG8_BAR __builtin_amdgcn_s_barrier()
; #define PG8_SCHED __builtin_amdgcn_sched_barrier(0)
; template <class Epi, class Sched, bool ALIGN_EPI = false, bool SP2 = false>
; __device__ __forceinline__ void gemm_phase(PG8_LAS unsigned char* lds, const Gemm g, const Sched& S, const Epi& E) {
;     ...
;         const char* nA = has_next ? (const char*)g.A + (size_t)nxt.pm * tstep : cA; const char* nB = has_next ? (const char*)g.Bt + (size_t)nxt.pn * tstep : cB;
;         for (int t = 0; t < nt; t += 2) {
;             const bool last = (t == nt - 2);
;             const char* a1 = cA + (size_t)(t + 1) * kstepA;
;             const char* a2 = last ? nA : cA + (size_t)(t + 2) * kstepA; const char* b2 = last ? nB : cB + (size_t)(t + 2) * kstep;
;             const char* a3 = a2 + kstepA; const char* b3 = b2 + kstep;
;             if (last && has_next) S.a_ready(nxt);
;             if constexpr (SP2) {
;             PG8_LDB(B0, 0, 0); PG8_LDB(B1, 0, 1); PG8_SCHED; PG8_LDA(At, 0, 0); PG8_STAGE(PG8_SA(1, 1), a1 + hstep, voffA);
;             PG8_WAIT_V(8); PG8_WAIT_L(0); PG8_BAR; PG8_MMA(0, 0, At, B0); PG8_MMA(0, 1, At, B1); PG8_BAR; PG8_SCHED;
;     ...
; #pragma unroll
;         for (int a = 0; a < 2; ++a)
; #pragma unroll
;             for (int b = 0; b < 2; ++b)
; #pragma unroll
;                 for (int m = 0; m < 4; ++m)
; #pragma unroll
;                     for (int n = 0; n < 2; ++n) acc[a][b][m][n] = (f32x4){0.f, 0.f, 0.f, 0.f};
.LBB0_408:
	s_ashr_i32 s11, s10, 31
	s_lshl_b64 s[12:13], s[10:11], 19
	s_add_u32 s12, s30, s12
	s_addc_u32 s13, s31, s13
	s_and_b64 s[18:19], s[4:5], exec
	s_cselect_b32 s11, s13, s23
	s_cselect_b32 s53, s12, s22
	s_ashr_i32 s9, s8, 31
	s_lshl_b64 s[18:19], s[8:9], 19
	s_add_u32 s18, s37, s18
	s_addc_u32 s19, s44, s19
	s_and_b64 s[26:27], s[4:5], exec
	s_cselect_b32 s9, s19, s25
	s_cselect_b32 s54, s18, s24
	s_add_u32 s55, s24, 0x100
	v_mov_b64_e32 v[2:3], 0
	v_mov_b64_e32 v[4:5], 0
	v_mov_b64_e32 v[6:7], 0
	v_mov_b64_e32 v[8:9], 0
	v_mov_b64_e32 v[10:11], 0
	v_mov_b64_e32 v[12:13], 0
	v_mov_b64_e32 v[14:15], 0
	v_mov_b64_e32 v[16:17], 0
	v_mov_b64_e32 v[18:19], 0
	v_mov_b64_e32 v[20:21], 0
	v_mov_b64_e32 v[22:23], 0
	v_mov_b64_e32 v[24:25], 0
	v_mov_b64_e32 v[26:27], 0
	v_mov_b64_e32 v[28:29], 0
	v_mov_b64_e32 v[30:31], 0
	v_mov_b64_e32 v[32:33], 0
	v_mov_b64_e32 v[34:35], 0
	v_mov_b64_e32 v[36:37], 0
	v_mov_b64_e32 v[38:39], 0
	v_mov_b64_e32 v[40:41], 0
	v_mov_b64_e32 v[42:43], 0
	v_mov_b64_e32 v[44:45], 0
	v_mov_b64_e32 v[46:47], 0
	v_mov_b64_e32 v[48:49], 0
	v_mov_b64_e32 v[50:51], 0
	v_mov_b64_e32 v[52:53], 0
	v_mov_b64_e32 v[54:55], 0
	v_mov_b64_e32 v[56:57], 0
	v_mov_b64_e32 v[58:59], 0
	v_mov_b64_e32 v[60:61], 0
	v_mov_b64_e32 v[62:63], 0
	v_mov_b64_e32 v[64:65], 0
	v_mov_b64_e32 v[66:67], 0
	v_mov_b64_e32 v[68:69], 0
	v_mov_b64_e32 v[70:71], 0
	v_mov_b64_e32 v[72:73], 0
	v_mov_b64_e32 v[74:75], 0
	v_mov_b64_e32 v[76:77], 0
	v_mov_b64_e32 v[78:79], 0
	v_mov_b64_e32 v[80:81], 0
	v_mov_b64_e32 v[82:83], 0
	v_mov_b64_e32 v[84:85], 0
	v_mov_b64_e32 v[86:87], 0
	v_mov_b64_e32 v[88:89], 0
	v_mov_b64_e32 v[90:91], 0
	v_mov_b64_e32 v[92:93], 0
	v_mov_b64_e32 v[94:95], 0
	v_mov_b64_e32 v[96:97], 0
	v_mov_b64_e32 v[98:99], 0
	v_mov_b64_e32 v[100:101], 0
	v_mov_b64_e32 v[102:103], 0
	v_mov_b64_e32 v[104:105], 0
	v_mov_b64_e32 v[106:107], 0
	v_mov_b64_e32 v[108:109], 0
	v_mov_b64_e32 v[110:111], 0
	v_mov_b64_e32 v[112:113], 0
	v_mov_b64_e32 v[114:115], 0
	v_mov_b64_e32 v[116:117], 0
	v_mov_b64_e32 v[118:119], 0
	v_mov_b64_e32 v[120:121], 0
	v_mov_b64_e32 v[122:123], 0
	v_mov_b64_e32 v[124:125], 0
	v_mov_b64_e32 v[126:127], 0
	v_mov_b64_e32 v[128:129], 0
	s_addc_u32 s56, s25, 0
	s_mov_b32 s57, -2
.LBB0_409:
	s_add_u32 s24, s22, 0x8000
	s_addc_u32 s25, s23, 0
	s_cmp_eq_u32 s57, 12
	s_cselect_b32 s42, s53, s24
	s_cselect_b32 s43, s11, s25
	s_cselect_b32 s40, s54, s55
	s_cselect_b32 s41, s9, s56
	s_add_u32 s26, s42, 0x4000
	s_addc_u32 s27, s43, 0
	v_add_u32_e32 v145, s76, v142
	s_add_i32 s58, 0, 0x14000
	ds_read_b128 v[146:149], v145
	ds_read_b128 v[150:153], v145 offset:1024
	ds_read_b128 v[160:163], v145 offset:2048
	ds_read_b128 v[164:167], v145 offset:3072
	v_add_u32_e32 v145, s58, v142
	ds_read_b128 v[168:171], v145
	ds_read_b128 v[172:175], v145 offset:1024
	ds_read_b128 v[176:179], v145 offset:2048
	ds_read_b128 v[180:183], v145 offset:3072
	v_lshl_add_u64 v[230:231], s[22:23], 0, v[140:141]
	s_add_i32 m0, s45, 0xc000
	ds_read_b128 v[184:187], v144
	ds_read_b128 v[188:191], v144 offset:1024
	ds_read_b128 v[206:209], v144 offset:2048
	ds_read_b128 v[210:213], v144 offset:3072
	ds_read_b128 v[214:217], v144 offset:4096
	ds_read_b128 v[218:221], v144 offset:5120
	ds_read_b128 v[222:225], v144 offset:6144
	ds_read_b128 v[226:229], v144 offset:7168
	global_load_lds_dwordx4 v[230:231], off
	v_lshl_add_u64 v[230:231], s[22:23], 0, v[138:139]
	s_add_i32 m0, s45, 0xe000
	s_nop 0
	global_load_lds_dwordx4 v[230:231], off
	s_waitcnt vmcnt(8)
	s_waitcnt lgkmcnt(0)
	s_barrier
	s_setprio 1
	s_waitcnt lgkmcnt(0)
	v_mfma_f32_16x16x32_bf16 v[126:129], v[146:149], v[184:187], v[126:129]
	v_mfma_f32_16x16x32_bf16 v[126:129], v[150:153], v[188:191], v[126:129]
	v_mfma_f32_16x16x32_bf16 v[118:121], v[164:167], v[188:191], v[118:121]
	v_mfma_f32_16x16x32_bf16 v[118:121], v[160:163], v[184:187], v[118:121]
	v_mfma_f32_16x16x32_bf16 v[102:105], v[160:163], v[206:209], v[102:105]
	v_mfma_f32_16x16x32_bf16 v[102:105], v[164:167], v[210:213], v[102:105]
	v_mfma_f32_16x16x32_bf16 v[110:113], v[150:153], v[210:213], v[110:113]
	v_mfma_f32_16x16x32_bf16 v[110:113], v[146:149], v[206:209], v[110:113]
	v_mfma_f32_16x16x32_bf16 v[94:97], v[146:149], v[214:217], v[94:97]
	v_mfma_f32_16x16x32_bf16 v[94:97], v[150:153], v[218:221], v[94:97]
	v_mfma_f32_16x16x32_bf16 v[86:89], v[164:167], v[218:221], v[86:89]
	v_mfma_f32_16x16x32_bf16 v[86:89], v[160:163], v[214:217], v[86:89]
	v_mfma_f32_16x16x32_bf16 v[70:73], v[160:163], v[222:225], v[70:73]
	v_mfma_f32_16x16x32_bf16 v[70:73], v[164:167], v[226:229], v[70:73]
	v_mfma_f32_16x16x32_bf16 v[78:81], v[150:153], v[226:229], v[78:81]
	v_mfma_f32_16x16x32_bf16 v[78:81], v[146:149], v[222:225], v[78:81]
	s_setprio 0
	s_setprio 1
	v_mfma_f32_16x16x32_bf16 v[122:125], v[168:171], v[184:187], v[122:125]
	v_mfma_f32_16x16x32_bf16 v[122:125], v[172:175], v[188:191], v[122:125]
	v_mfma_f32_16x16x32_bf16 v[114:117], v[180:183], v[188:191], v[114:117]
	v_mfma_f32_16x16x32_bf16 v[114:117], v[176:179], v[184:187], v[114:117]
	v_mfma_f32_16x16x32_bf16 v[98:101], v[176:179], v[206:209], v[98:101]
	v_mfma_f32_16x16x32_bf16 v[98:101], v[180:183], v[210:213], v[98:101]
	v_mfma_f32_16x16x32_bf16 v[106:109], v[172:175], v[210:213], v[106:109]
	v_mfma_f32_16x16x32_bf16 v[106:109], v[168:171], v[206:209], v[106:109]
	v_mfma_f32_16x16x32_bf16 v[90:93], v[168:171], v[214:217], v[90:93]
	v_mfma_f32_16x16x32_bf16 v[90:93], v[172:175], v[218:221], v[90:93]
	v_mfma_f32_16x16x32_bf16 v[82:85], v[180:183], v[218:221], v[82:85]
	v_mfma_f32_16x16x32_bf16 v[82:85], v[176:179], v[214:217], v[82:85]
	v_mfma_f32_16x16x32_bf16 v[66:69], v[176:179], v[222:225], v[66:69]
	v_mfma_f32_16x16x32_bf16 v[66:69], v[180:183], v[226:229], v[66:69]
	v_mfma_f32_16x16x32_bf16 v[74:77], v[172:175], v[226:229], v[74:77]
	v_mfma_f32_16x16x32_bf16 v[74:77], v[168:171], v[222:225], v[74:77]
	s_setprio 0
	s_barrier
; #define PG8_STAGE(bufoff, gbase, voff) do { _Pragma("unroll") for (int _i = 0; _i < 2; ++_i) \
;         __builtin_amdgcn_global_load_lds((const unsigned*)((const char*)(gbase) + (voff)[_i]), (PG8_LAS unsigned*)(lds + (bufoff) + ldsw + _i * 8192), 16, 0, 0); } while (0)
; #define PG8_LDA(dst, b, h) do { _Pragma("unroll") for (int m = 0; m < 4; ++m) _Pragma("unroll") for (int k = 0; k < 2; ++k) dst[m][k] = *(const PG8_LAS bf16x8*)(lds + PG8_SA(b, h) + aoff + m * 2048 + k * 1024); } while (0)
; #define PG8_LDB(dst, b, h) do { _Pragma("unroll") for (int n = 0; n < 2; ++n) _Pragma("unroll") for (int k = 0; k < 2; ++k) dst[n][k] = *(const PG8_LAS bf16x8*)(lds + PG8_SB(b, h) + boff + n * 2048 + k * 1024); } while (0)
; #define PG8_MMA(ai, bj, At, Bt) do { __builtin_amdgcn_s_setprio(1); _Pragma("unroll") for (int m = 0; m < 4; ++m) _Pragma("unroll") for (int n = 0; n < 2; ++n) _Pragma("unroll") for (int k = 0; k < 2; ++k) \
;         acc[ai][bj][m][n] = __builtin_amdgcn_mfma_f32_16x16x32_bf16(Bt[n][k], At[m][k], acc[ai][bj][m][n], 0, 0, 0); __builtin_amdgcn_s_setprio(0); } while (0)
; #define PG8_WAIT_V(n) asm volatile("s_waitcnt vmcnt(" #n ")" ::: "memory")
; #define PG8_WAIT_L(n) asm volatile("s_waitcnt lgkmcnt(" #n ")" ::: "memory")
; #define PG8_BAR __builtin_amdgcn_s_barrier()
; #define PG8_SCHED __builtin_amdgcn_sched_barrier(0)
; template <class Epi, class Sched, bool ALIGN_EPI = false, bool SP2 = false>
; __device__ __forceinline__ void gemm_phase(PG8_LAS unsigned char* lds, const Gemm g, const Sched& S, const Epi& E) {
;     ...
;             PG8_LDA(At, 0, 1); PG8_STAGE(PG8_SB(0, 0), b2, voffB); PG8_STAGE(PG8_SB(0, 1), b2 + hstep, voffB); PG8_STAGE(PG8_SA(0, 0), a2, voffA);
;             PG8_WAIT_V(8); PG8_WAIT_L(0); PG8_BAR; PG8_MMA(1, 0, At, B0); PG8_MMA(1, 1, At, B1); PG8_BAR; PG8_SCHED;
;             PG8_LDB(B0, 1, 0); PG8_LDB(B1, 1, 1); PG8_SCHED; PG8_LDA(At, 1, 0); PG8_STAGE(PG8_SA(0, 1), a2 + hstep, voffA);
	s_add_i32 s22, s76, s29
	v_lshl_add_u64 v[230:231], s[40:41], 0, v[0:1]
	s_mov_b32 m0, s22
	ds_read_b128 v[184:187], v144 offset:16384
	ds_read_b128 v[188:191], v144 offset:17408
	ds_read_b128 v[206:209], v144 offset:18432
	ds_read_b128 v[210:213], v144 offset:19456
	ds_read_b128 v[214:217], v144 offset:20480
	ds_read_b128 v[218:221], v144 offset:21504
	ds_read_b128 v[222:225], v144 offset:22528
	ds_read_b128 v[226:229], v144 offset:23552
	global_load_lds_dwordx4 v[230:231], off
	s_add_i32 m0, s22, 0x2000
	s_add_u32 s22, s40, 0x40000
	v_lshl_add_u64 v[232:233], s[40:41], 0, v[130:131]
	s_addc_u32 s23, s41, 0
	s_add_i32 s58, s58, s29
	global_load_lds_dwordx4 v[232:233], off
	v_lshl_add_u64 v[234:235], s[22:23], 0, v[0:1]
	s_mov_b32 m0, s58
	s_nop 0
	global_load_lds_dwordx4 v[234:235], off
	v_lshl_add_u64 v[234:235], s[22:23], 0, v[130:131]
	s_add_i32 m0, s58, 0x2000
	s_nop 0
	global_load_lds_dwordx4 v[234:235], off
	v_lshl_add_u64 v[234:235], s[42:43], 0, v[134:135]
	s_mov_b32 m0, s45
	s_nop 0
	global_load_lds_dwordx4 v[234:235], off
	v_lshl_add_u64 v[234:235], s[42:43], 0, v[132:133]
	s_mov_b32 m0, s46
	s_nop 0
	global_load_lds_dwordx4 v[234:235], off
	s_waitcnt vmcnt(8)
	s_waitcnt lgkmcnt(0)
	s_barrier
	s_setprio 1
	s_waitcnt lgkmcnt(0)
	v_mfma_f32_16x16x32_bf16 v[62:65], v[146:149], v[184:187], v[62:65]
	v_mfma_f32_16x16x32_bf16 v[62:65], v[150:153], v[188:191], v[62:65]
	v_mfma_f32_16x16x32_bf16 v[54:57], v[164:167], v[188:191], v[54:57]
	v_mfma_f32_16x16x32_bf16 v[54:57], v[160:163], v[184:187], v[54:57]
	v_mfma_f32_16x16x32_bf16 v[38:41], v[160:163], v[206:209], v[38:41]
	v_mfma_f32_16x16x32_bf16 v[38:41], v[164:167], v[210:213], v[38:41]
	v_mfma_f32_16x16x32_bf16 v[46:49], v[150:153], v[210:213], v[46:49]
	v_mfma_f32_16x16x32_bf16 v[46:49], v[146:149], v[206:209], v[46:49]
	v_mfma_f32_16x16x32_bf16 v[30:33], v[146:149], v[214:217], v[30:33]
	v_mfma_f32_16x16x32_bf16 v[30:33], v[150:153], v[218:221], v[30:33]
	v_mfma_f32_16x16x32_bf16 v[22:25], v[164:167], v[218:221], v[22:25]
	v_mfma_f32_16x16x32_bf16 v[22:25], v[160:163], v[214:217], v[22:25]
	v_mfma_f32_16x16x32_bf16 v[6:9], v[160:163], v[222:225], v[6:9]
	v_mfma_f32_16x16x32_bf16 v[6:9], v[164:167], v[226:229], v[6:9]
	v_mfma_f32_16x16x32_bf16 v[14:17], v[150:153], v[226:229], v[14:17]
	v_mfma_f32_16x16x32_bf16 v[14:17], v[146:149], v[222:225], v[14:17]
	s_setprio 0
	s_setprio 1
	v_mfma_f32_16x16x32_bf16 v[58:61], v[168:171], v[184:187], v[58:61]
	v_mfma_f32_16x16x32_bf16 v[58:61], v[172:175], v[188:191], v[58:61]
	v_mfma_f32_16x16x32_bf16 v[50:53], v[180:183], v[188:191], v[50:53]
	v_mfma_f32_16x16x32_bf16 v[50:53], v[176:179], v[184:187], v[50:53]
	v_mfma_f32_16x16x32_bf16 v[34:37], v[176:179], v[206:209], v[34:37]
	v_mfma_f32_16x16x32_bf16 v[34:37], v[180:183], v[210:213], v[34:37]
	v_mfma_f32_16x16x32_bf16 v[42:45], v[172:175], v[210:213], v[42:45]
	v_mfma_f32_16x16x32_bf16 v[42:45], v[168:171], v[206:209], v[42:45]
	v_mfma_f32_16x16x32_bf16 v[26:29], v[168:171], v[214:217], v[26:29]
	v_mfma_f32_16x16x32_bf16 v[26:29], v[172:175], v[218:221], v[26:29]
	v_mfma_f32_16x16x32_bf16 v[18:21], v[180:183], v[218:221], v[18:21]
	v_mfma_f32_16x16x32_bf16 v[18:21], v[176:179], v[214:217], v[18:21]
	v_mfma_f32_16x16x32_bf16 v[2:5], v[176:179], v[222:225], v[2:5]
	v_mfma_f32_16x16x32_bf16 v[2:5], v[180:183], v[226:229], v[2:5]
	v_mfma_f32_16x16x32_bf16 v[10:13], v[172:175], v[226:229], v[10:13]
	v_mfma_f32_16x16x32_bf16 v[10:13], v[168:171], v[222:225], v[10:13]
	s_setprio 0
	s_barrier
	s_add_i32 s58, 0, 0x18000
	v_add_u32_e32 v145, s58, v142
	s_add_i32 s59, 0, 0x1c000
	ds_read_b128 v[146:149], v145
	ds_read_b128 v[150:153], v145 offset:1024
	ds_read_b128 v[160:163], v145 offset:2048
	ds_read_b128 v[164:167], v145 offset:3072
	v_add_u32_e32 v145, s59, v142
	ds_read_b128 v[168:171], v145
	ds_read_b128 v[172:175], v145 offset:1024
	ds_read_b128 v[176:179], v145 offset:2048
	ds_read_b128 v[180:183], v145 offset:3072
	s_add_u32 s22, s42, 0x40000
	s_addc_u32 s23, s43, 0
	s_mov_b32 m0, s47
	v_lshl_add_u64 v[234:235], s[22:23], 0, v[134:135]
	ds_read_b128 v[184:187], v144 offset:32768
	ds_read_b128 v[188:191], v144 offset:33792
	ds_read_b128 v[206:209], v144 offset:34816
	ds_read_b128 v[210:213], v144 offset:35840
	ds_read_b128 v[214:217], v144 offset:36864
	ds_read_b128 v[218:221], v144 offset:37888
	ds_read_b128 v[222:225], v144 offset:38912
	ds_read_b128 v[226:229], v144 offset:39936
	global_load_lds_dwordx4 v[234:235], off
	v_lshl_add_u64 v[234:235], s[22:23], 0, v[132:133]
	s_mov_b32 m0, s48
	s_nop 0
	global_load_lds_dwordx4 v[234:235], off
	s_waitcnt vmcnt(8)
	s_waitcnt lgkmcnt(0)
	s_barrier
; #define PG8_STAGE(bufoff, gbase, voff) do { _Pragma("unroll") for (int _i = 0; _i < 2; ++_i) \
;         __builtin_amdgcn_global_load_lds((const unsigned*)((const char*)(gbase) + (voff)[_i]), (PG8_LAS unsigned*)(lds + (bufoff) + ldsw + _i * 8192), 16, 0, 0); } while (0)
; #define PG8_LDA(dst, b, h) do { _Pragma("unroll") for (int m = 0; m < 4; ++m) _Pragma("unroll") for (int k = 0; k < 2; ++k) dst[m][k] = *(const PG8_LAS bf16x8*)(lds + PG8_SA(b, h) + aoff + m * 2048 + k * 1024); } while (0)
; #define PG8_MMA(ai, bj, At, Bt) do { __builtin_amdgcn_s_setprio(1); _Pragma("unroll") for (int m = 0; m < 4; ++m) _Pragma("unroll") for (int n = 0; n < 2; ++n) _Pragma("unroll") for (int k = 0; k < 2; ++k) \
;         acc[ai][bj][m][n] = __builtin_amdgcn_mfma_f32_16x16x32_bf16(Bt[n][k], At[m][k], acc[ai][bj][m][n], 0, 0, 0); __builtin_amdgcn_s_setprio(0); } while (0)
; #define PG8_WAIT_V(n) asm volatile("s_waitcnt vmcnt(" #n ")" ::: "memory")
; #define PG8_WAIT_L(n) asm volatile("s_waitcnt lgkmcnt(" #n ")" ::: "memory")
; #define PG8_BAR __builtin_amdgcn_s_barrier()
; #define PG8_SCHED __builtin_amdgcn_sched_barrier(0)
; template <class Epi, class Sched, bool ALIGN_EPI = false, bool SP2 = false>
; __device__ __forceinline__ void gemm_phase(PG8_LAS unsigned char* lds, const Gemm g, const Sched& S, const Epi& E) {
;     ...
;             PG8_WAIT_V(8); PG8_WAIT_L(0); PG8_BAR; PG8_MMA(0, 0, At, B0); PG8_MMA(0, 1, At, B1); PG8_BAR; PG8_SCHED;
;             PG8_LDA(At, 1, 1); PG8_STAGE(PG8_SB(1, 0), b3, voffB); PG8_STAGE(PG8_SB(1, 1), b3 + hstep, voffB); PG8_STAGE(PG8_SA(1, 0), a3, voffA);
;             PG8_WAIT_V(8); PG8_WAIT_L(0); PG8_BAR; PG8_MMA(1, 0, At, B0); PG8_MMA(1, 1, At, B1); PG8_BAR; PG8_SCHED;
	s_setprio 1
	s_waitcnt lgkmcnt(0)
	v_mfma_f32_16x16x32_bf16 v[126:129], v[146:149], v[184:187], v[126:129]
	v_mfma_f32_16x16x32_bf16 v[126:129], v[150:153], v[188:191], v[126:129]
	v_mfma_f32_16x16x32_bf16 v[118:121], v[164:167], v[188:191], v[118:121]
	v_mfma_f32_16x16x32_bf16 v[118:121], v[160:163], v[184:187], v[118:121]
	v_mfma_f32_16x16x32_bf16 v[102:105], v[160:163], v[206:209], v[102:105]
	v_mfma_f32_16x16x32_bf16 v[102:105], v[164:167], v[210:213], v[102:105]
	v_mfma_f32_16x16x32_bf16 v[110:113], v[150:153], v[210:213], v[110:113]
	v_mfma_f32_16x16x32_bf16 v[110:113], v[146:149], v[206:209], v[110:113]
	v_mfma_f32_16x16x32_bf16 v[94:97], v[146:149], v[214:217], v[94:97]
	v_mfma_f32_16x16x32_bf16 v[94:97], v[150:153], v[218:221], v[94:97]
	v_mfma_f32_16x16x32_bf16 v[86:89], v[164:167], v[218:221], v[86:89]
	v_mfma_f32_16x16x32_bf16 v[86:89], v[160:163], v[214:217], v[86:89]
	v_mfma_f32_16x16x32_bf16 v[70:73], v[160:163], v[222:225], v[70:73]
	v_mfma_f32_16x16x32_bf16 v[70:73], v[164:167], v[226:229], v[70:73]
	v_mfma_f32_16x16x32_bf16 v[78:81], v[150:153], v[226:229], v[78:81]
	v_mfma_f32_16x16x32_bf16 v[78:81], v[146:149], v[222:225], v[78:81]
	s_setprio 0
	s_setprio 1
	v_mfma_f32_16x16x32_bf16 v[122:125], v[168:171], v[184:187], v[122:125]
	v_mfma_f32_16x16x32_bf16 v[122:125], v[172:175], v[188:191], v[122:125]
	v_mfma_f32_16x16x32_bf16 v[114:117], v[180:183], v[188:191], v[114:117]
	v_mfma_f32_16x16x32_bf16 v[114:117], v[176:179], v[184:187], v[114:117]
	v_mfma_f32_16x16x32_bf16 v[98:101], v[176:179], v[206:209], v[98:101]
	v_mfma_f32_16x16x32_bf16 v[98:101], v[180:183], v[210:213], v[98:101]
	v_mfma_f32_16x16x32_bf16 v[106:109], v[172:175], v[210:213], v[106:109]
	v_mfma_f32_16x16x32_bf16 v[106:109], v[168:171], v[206:209], v[106:109]
	v_mfma_f32_16x16x32_bf16 v[90:93], v[168:171], v[214:217], v[90:93]
	v_mfma_f32_16x16x32_bf16 v[90:93], v[172:175], v[218:221], v[90:93]
	v_mfma_f32_16x16x32_bf16 v[82:85], v[180:183], v[218:221], v[82:85]
	v_mfma_f32_16x16x32_bf16 v[82:85], v[176:179], v[214:217], v[82:85]
	v_mfma_f32_16x16x32_bf16 v[66:69], v[176:179], v[222:225], v[66:69]
	v_mfma_f32_16x16x32_bf16 v[66:69], v[180:183], v[226:229], v[66:69]
	v_mfma_f32_16x16x32_bf16 v[74:77], v[172:175], v[226:229], v[74:77]
	v_mfma_f32_16x16x32_bf16 v[74:77], v[168:171], v[222:225], v[74:77]
	s_setprio 0
	s_barrier
	s_add_i32 s22, s58, s29
	v_lshl_add_u64 v[230:231], v[230:231], 0, s[38:39]
	s_mov_b32 m0, s22
	ds_read_b128 v[184:187], v144 offset:49152
	ds_read_b128 v[188:191], v144 offset:50176
	ds_read_b128 v[206:209], v144 offset:51200
	ds_read_b128 v[210:213], v144 offset:52224
	ds_read_b128 v[214:217], v144 offset:53248
	ds_read_b128 v[218:221], v144 offset:54272
	ds_read_b128 v[222:225], v144 offset:55296
	ds_read_b128 v[226:229], v144 offset:56320
	global_load_lds_dwordx4 v[230:231], off
	s_add_i32 m0, s22, 0x2000
	s_add_u32 s22, s40, 0x40080
	v_lshl_add_u64 v[230:231], v[232:233], 0, s[38:39]
	s_addc_u32 s23, s41, 0
	s_add_i32 s40, s59, s29
	global_load_lds_dwordx4 v[230:231], off
	v_lshl_add_u64 v[230:231], s[22:23], 0, v[0:1]
	s_mov_b32 m0, s40
	s_nop 0
	global_load_lds_dwordx4 v[230:231], off
	v_lshl_add_u64 v[230:231], s[22:23], 0, v[130:131]
	s_add_i32 m0, s40, 0x2000
	s_nop 0
	global_load_lds_dwordx4 v[230:231], off
	v_lshl_add_u64 v[230:231], s[26:27], 0, v[134:135]
	s_mov_b32 m0, s49
	s_nop 0
	global_load_lds_dwordx4 v[230:231], off
	v_lshl_add_u64 v[230:231], s[26:27], 0, v[132:133]
	s_mov_b32 m0, s50
	s_nop 0
	global_load_lds_dwordx4 v[230:231], off
	s_waitcnt vmcnt(8)
	s_waitcnt lgkmcnt(0)
	s_barrier
	s_setprio 1
	s_waitcnt lgkmcnt(0)
	v_mfma_f32_16x16x32_bf16 v[62:65], v[146:149], v[184:187], v[62:65]
	v_mfma_f32_16x16x32_bf16 v[62:65], v[150:153], v[188:191], v[62:65]
	v_mfma_f32_16x16x32_bf16 v[54:57], v[164:167], v[188:191], v[54:57]
	v_mfma_f32_16x16x32_bf16 v[54:57], v[160:163], v[184:187], v[54:57]
	v_mfma_f32_16x16x32_bf16 v[38:41], v[160:163], v[206:209], v[38:41]
	v_mfma_f32_16x16x32_bf16 v[38:41], v[164:167], v[210:213], v[38:41]
	v_mfma_f32_16x16x32_bf16 v[46:49], v[150:153], v[210:213], v[46:49]
	v_mfma_f32_16x16x32_bf16 v[46:49], v[146:149], v[206:209], v[46:49]
	v_mfma_f32_16x16x32_bf16 v[30:33], v[146:149], v[214:217], v[30:33]
	v_mfma_f32_16x16x32_bf16 v[30:33], v[150:153], v[218:221], v[30:33]
	v_mfma_f32_16x16x32_bf16 v[22:25], v[164:167], v[218:221], v[22:25]
	v_mfma_f32_16x16x32_bf16 v[22:25], v[160:163], v[214:217], v[22:25]
	v_mfma_f32_16x16x32_bf16 v[6:9], v[160:163], v[222:225], v[6:9]
	v_mfma_f32_16x16x32_bf16 v[6:9], v[164:167], v[226:229], v[6:9]
	v_mfma_f32_16x16x32_bf16 v[14:17], v[150:153], v[226:229], v[14:17]
	v_mfma_f32_16x16x32_bf16 v[14:17], v[146:149], v[222:225], v[14:17]
	s_setprio 0
	s_setprio 1
	v_mfma_f32_16x16x32_bf16 v[58:61], v[168:171], v[184:187], v[58:61]
	v_mfma_f32_16x16x32_bf16 v[58:61], v[172:175], v[188:191], v[58:61]
	v_mfma_f32_16x16x32_bf16 v[50:53], v[180:183], v[188:191], v[50:53]
	v_mfma_f32_16x16x32_bf16 v[50:53], v[176:179], v[184:187], v[50:53]
	v_mfma_f32_16x16x32_bf16 v[34:37], v[176:179], v[206:209], v[34:37]
	v_mfma_f32_16x16x32_bf16 v[34:37], v[180:183], v[210:213], v[34:37]
	v_mfma_f32_16x16x32_bf16 v[42:45], v[172:175], v[210:213], v[42:45]
	v_mfma_f32_16x16x32_bf16 v[42:45], v[168:171], v[206:209], v[42:45]
	v_mfma_f32_16x16x32_bf16 v[26:29], v[168:171], v[214:217], v[26:29]
	v_mfma_f32_16x16x32_bf16 v[26:29], v[172:175], v[218:221], v[26:29]
	v_mfma_f32_16x16x32_bf16 v[18:21], v[180:183], v[218:221], v[18:21]
	v_mfma_f32_16x16x32_bf16 v[18:21], v[176:179], v[214:217], v[18:21]
	v_mfma_f32_16x16x32_bf16 v[2:5], v[176:179], v[222:225], v[2:5]
	v_mfma_f32_16x16x32_bf16 v[2:5], v[180:183], v[226:229], v[2:5]
	v_mfma_f32_16x16x32_bf16 v[10:13], v[172:175], v[226:229], v[10:13]
	v_mfma_f32_16x16x32_bf16 v[10:13], v[168:171], v[222:225], v[10:13]
	s_setprio 0
	s_barrier
	s_add_i32 s57, s57, 2
	s_add_u32 s55, s55, 0x100
	s_addc_u32 s56, s56, 0
	s_cmp_gt_u32 s57, 13
	s_mov_b64 s[22:23], s[24:25]
	s_cbranch_scc0 .LBB0_409
	s_and_b64 vcc, exec, s[6:7]
	s_cbranch_vccz .LBB0_412
	s_barrier
